# speedup vs baseline: 1.0341x; 1.0341x over previous
; template <int MF, int NF>
; __device__ __forceinline__ void gemm_issue_first(int zz, const u16* __restrict__ Wt, int ldw, const u16* __restrict__ Act, int lda,
;                                                  char* shm) {
;     ...
;   const int tid = TIDX, wid = tid >> 6, lane = tid & 63;
;   const int sb = lane * 16;
;   const int swz = sb ^ (((sb >> 9) & 1) << 5);
;   const int rr = swz >> 6, cc = (swz & 63) >> 1;
;   const unsigned voffA = (unsigned)(((wid >> 1) * 16 + rr) * ldw + (wid & 1) * 32 + cc);
;   const unsigned voffB = (unsigned)(((wid >> 1) * 16 + rr) * lda + (wid & 1) * 32 + cc);
; #pragma unroll
;   for (int i = 0; i < NLD; ++i) {
;     const u16* src = (i < NLA) ? (Wt + (long)(i * 64) * ldw + voffA) : (Act + (long)((i - NLA) * 64) * lda + voffB);
;     __builtin_amdgcn_global_load_lds((const unsigned*)src, (unsigned*)(shm + (i * 8 + wid) * 1024), 16, 0, 0);
;   }
; template <int EPI>
; __device__ __forceinline__ void gemm_phase(int zz, const u16* __restrict__ Wt, const u16* __restrict__ Act, int K, int lda, int nColTiles,
;                            u16* __restrict__ Out, int ldo, int nvalid, char* shm) {
;     ...
;   const int ntiles = nT * nColTiles;
;   int tile = virt_id();
;   __syncthreads();
;   if (tile < ntiles) {
;     int gidx = tile / (8 * nColTiles), rem = tile % (8 * nColTiles);
;     int pm = gidx * 8 + (rem & 7), pn = rem >> 3;
;     gemm_issue_first<8, 4>(zz, Wt + (long)(pn * 256) * K, K, Act + (long)(pm * 256) * lda, lda, shm);
;   }
.LBB0_220:
	v_writelane_b32 v254, s36, 12
	v_writelane_b32 v254, s37, 13
	v_writelane_b32 v254, s38, 14
	v_writelane_b32 v254, s39, 15
	v_writelane_b32 v254, s40, 16
	v_writelane_b32 v254, s41, 17
	v_writelane_b32 v254, s42, 18
	s_cmpk_gt_i32 s15, 0xaff
	s_barrier
	s_cbranch_scc1 .LBB0_227
	s_cmp_eq_u32 s20, 1
	s_cselect_b32 s2, 0, 0x2600000
	s_add_u32 s2, s64, s2
	s_mul_hi_i32 s4, s15, 0x2e8ba2e9
	s_addc_u32 s3, s65, 0
	s_mov_b64 s[40:41], s[2:3]
	s_lshr_b32 s5, s4, 31
	s_ashr_i32 s4, s4, 5
	s_add_i32 s6, s4, s5
	s_mul_i32 s4, s6, 0xb0
	s_sub_i32 s7, s15, s4
	s_lshl_b32 s4, s7, 5
	s_and_b32 s4, s4, 0xffffff00
	s_ashr_i32 s5, s4, 31
	s_lshl_b64 s[4:5], s[4:5], 11
	s_add_u32 s4, s2, s4
	s_waitcnt vmcnt(0)
	v_lshlrev_b32_e32 v0, 4, v34
	s_waitcnt vmcnt(0)
	v_and_b32_e32 v2, 32, v34
	s_addc_u32 s5, s3, s5
	s_lshl_b32 s7, s7, 8
	v_bitop3_b32 v0, v0, v2, 48 bitop3:0x6c
	v_ashrrev_i32_e32 v12, 3, v34
	s_lshl_b32 s6, s6, 11
	s_and_b32 s7, s7, 0x700
	v_ashrrev_i32_e32 v10, 6, v34
	v_lshrrev_b32_e32 v3, 2, v34
	v_lshrrev_b32_e32 v11, 1, v0
	v_and_b32_e32 v0, 0x3ffff0, v12
	s_or_b32 s6, s7, s6
	v_and_or_b32 v0, v3, 15, v0
	v_lshlrev_b32_e32 v2, 5, v10
	s_ashr_i32 s7, s6, 31
	v_lshlrev_b32_e32 v0, 10, v0
	v_and_b32_e32 v13, 32, v2
	s_lshl_b64 s[6:7], s[6:7], 11
	v_or3_b32 v0, v0, v11, v13
	s_add_u32 s6, s66, s6
	v_lshlrev_b32_e32 v131, 10, v10
	v_lshlrev_b64 v[2:3], 1, v[0:1]
	s_addc_u32 s7, s67, s7
	v_lshl_add_u64 v[6:7], s[4:5], 0, v[2:3]
	v_readfirstlane_b32 s4, v131
	v_readfirstlane_b32 s42, v131
	s_cmp_ge_u32 s42, 0x1000
	s_cbranch_scc0 .Lprio_sw
	s_setprio 1
.Lprio_sw:
	v_add_u32_e32 v144, 0x2000, v131
	v_lshl_add_u64 v[4:5], s[6:7], 0, v[2:3]
	s_mov_b32 m0, s4
	s_mov_b64 s[6:7], 0x20000
	v_readfirstlane_b32 s4, v144
	v_add_u32_e32 v145, 0x4000, v131
	global_load_lds_dwordx4 v[6:7], off
	v_lshl_add_u64 v[8:9], v[6:7], 0, s[6:7]
	s_mov_b32 m0, s4
	s_mov_b64 s[8:9], 0x40000
	v_readfirstlane_b32 s4, v145
	v_add_u32_e32 v146, 0x6000, v131
	global_load_lds_dwordx4 v[8:9], off
	v_lshl_add_u64 v[8:9], v[6:7], 0, s[8:9]
	s_mov_b32 m0, s4
	s_mov_b64 s[10:11], 0x60000
	v_readfirstlane_b32 s4, v146
	v_add_u32_e32 v147, 0x8000, v131
	global_load_lds_dwordx4 v[8:9], off
	v_lshl_add_u64 v[6:7], v[6:7], 0, s[10:11]
	s_mov_b32 m0, s4
	v_readfirstlane_b32 s4, v147
	v_add_u32_e32 v148, 0xa000, v131
	global_load_lds_dwordx4 v[6:7], off
	s_mov_b32 m0, s4
	v_readfirstlane_b32 s4, v148
	v_add_u32_e32 v149, 0xc000, v131
	global_load_lds_dwordx4 v[4:5], off
	v_lshl_add_u64 v[6:7], v[4:5], 0, s[6:7]
	s_mov_b32 m0, s4
	v_readfirstlane_b32 s4, v149
	v_add_u32_e32 v150, 0xe000, v131
	global_load_lds_dwordx4 v[6:7], off
	v_lshl_add_u64 v[6:7], v[4:5], 0, s[8:9]
	s_mov_b32 m0, s4
	v_readfirstlane_b32 s4, v150
	global_load_lds_dwordx4 v[6:7], off
	v_lshl_add_u64 v[4:5], v[4:5], 0, s[10:11]
	s_mov_b32 m0, s4
	v_and_b32_e32 v0, 48, v34
	global_load_lds_dwordx4 v[4:5], off
	v_lshlrev_b32_e32 v4, 6, v34
	v_and_b32_e32 v5, 0x3c0, v4
	v_lshlrev_b32_e32 v7, 2, v34
	v_lshl_add_u64 v[132:133], s[66:67], 0, v[2:3]
	v_lshl_add_u64 v[134:135], s[2:3], 0, v[2:3]
	v_ashrrev_i32_e32 v2, 2, v34
	s_movk_i32 s4, 0xffc0
	v_or_b32_e32 v6, v5, v0
	v_and_b32_e32 v7, 32, v7
	v_and_b32_e32 v152, 0xffffc000, v4
	v_lshlrev_b32_e32 v4, 13, v10
	v_and_or_b32 v155, v2, s4, v0
	s_mov_b32 s4, 0x10000
	v_bitop3_b32 v151, v5, v7, v0 bitop3:0x36
	v_and_b32_e32 v153, 0x6000, v4
	v_bitop3_b32 v4, v6, s4, v7 bitop3:0xde
	v_lshlrev_b32_e32 v0, 10, v12
	s_movk_i32 s4, 0xc000
	v_lshlrev_b32_e32 v2, 8, v34
	v_and_or_b32 v0, v0, s4, v11
	v_and_b32_e32 v2, 0x3c00, v2
	v_or3_b32 v0, v0, v2, v13
	v_or_b32_e32 v5, 0x10000, v153
	v_lshlrev_b64 v[2:3], 1, v[0:1]
	v_and_b32_e32 v154, 0xcf, v34
	v_mov_b32_e32 v179, v2
	v_lshl_add_u64 v[136:137], s[2:3], 0, v[2:3]
	v_lshl_add_u64 v[138:139], s[66:67], 0, v[2:3]
	v_add_u32_e32 v0, v4, v152
	v_add_u32_e32 v156, v5, v151
	s_branch .LBB0_223

; template <int MF, int NF>
; __device__ __forceinline__ void gemm_main(int zz, f32x4 (&acc)[MF][NF], const u16* __restrict__ Wt, int ldw,
;                                           const u16* __restrict__ Act, int lda, int K, char* shm) {
;     ...
;   for (int t = 0; t < nt; ++t) {
;     const int cur = t & 1;
;     if (t + 1 < nt) {
; #pragma unroll
;       for (int i = 0; i < NLD; ++i) {
;         const u16* src = (i < NLA) ? (Wt + (long)(i * 64) * ldw + (t + 1) * 64 + voffA)
;                                    : (Act + (long)((i - NLA) * 64) * lda + (t + 1) * 64 + voffB);
;         __builtin_amdgcn_global_load_lds((const unsigned*)src, (unsigned*)(shm + (cur ^ 1) * STAGE_B + (i * 8 + wid) * 1024), 16, 0, 0);
;       }
;     }
;     const char* sbase = shm + cur * STAGE_B;
;     {
;       constexpr int D = (NF >= 4) ? 3 : ((MF >= 12) ? 6 : 4), RING = D + 1, NSTEP = 2 * MF;
;       bf16x8 Bf[2][NF], Ar[RING];
; #pragma unroll
;       for (int n = 0; n < NF; ++n) Bf[0][n] = *(const bf16x8*)(sbase + boff + (n * 2 + 0) * 1024);
; #pragma unroll
;       for (int j = 0; j < D; ++j) Ar[j % RING] = *(const bf16x8*)(sbase + aoff + ((j % MF) * 2 + (j / MF)) * 1024);
;       __builtin_amdgcn_sched_barrier(0);
;       __builtin_amdgcn_s_setprio(1);
; #pragma unroll
;       for (int i = 0; i < NSTEP; ++i) {
;         const int ks = i / MF, m = i % MF;
;         const int j = i + D;
;         if (j < NSTEP) {
;           const int ksj = j / MF, mj = j % MF;
;           if (mj == 0) {
; #pragma unroll
;             for (int n = 0; n < NF; ++n) Bf[ksj][n] = *(const bf16x8*)(sbase + boff + (n * 2 + ksj) * 1024);
;           }
;           Ar[j % RING] = *(const bf16x8*)(sbase + aoff + (mj * 2 + ksj) * 1024);
;         }
; #pragma unroll
;         for (int n = 0; n < NF; ++n) acc[m][n] = __builtin_amdgcn_mfma_f32_16x16x32_bf16(Ar[i % RING], Bf[ks][n], acc[m][n], 0, 0, 0);
;         __builtin_amdgcn_sched_barrier(0);
;       }
.LBB0_224:
	s_and_b32 s5, s3, 0x10000
	s_xor_b32 s8, s5, 0x10000
	s_add_i32 s8, s8, s42
	s_mov_b32 m0, s8
	v_or_b32_e32 v157, s5, v151
	v_add_u32_e32 v178, v157, v153
	v_add_u32_e32 v157, v157, v152
	ds_read_b128 v[174:177], v157
	ds_read_b128 v[158:161], v178 offset:32768
	ds_read_b128 v[162:165], v178 offset:34816
	ds_read_b128 v[166:169], v178 offset:36864
	ds_read_b128 v[170:173], v178 offset:38912
	ds_read_b128 v[192:195], v157 offset:2048
	ds_read_b128 v[196:199], v157 offset:4096
	s_nop 0
	s_waitcnt lgkmcnt(5)
	v_mfma_f32_16x16x32_bf16 v[126:129], v[174:177], v[158:161], v[126:129]
	ds_read_b128 v[200:203], v157 offset:6144
	s_waitcnt lgkmcnt(5)
	v_mfma_f32_16x16x32_bf16 v[122:125], v[174:177], v[162:165], v[122:125]
	global_load_lds_dwordx4 v179, s[36:37]
	s_waitcnt lgkmcnt(4)
	v_mfma_f32_16x16x32_bf16 v[118:121], v[174:177], v[166:169], v[118:121]
	s_add_u32 s36, s36, 0x20000
	s_addc_u32 s37, s37, 0
	s_addk_i32 m0, 0x2000
	s_waitcnt lgkmcnt(3)
	v_mfma_f32_16x16x32_bf16 v[114:117], v[174:177], v[170:173], v[114:117]
	s_waitcnt lgkmcnt(2)
	v_mfma_f32_16x16x32_bf16 v[110:113], v[192:195], v[158:161], v[110:113]
	ds_read_b128 v[174:177], v157 offset:8192
	v_mfma_f32_16x16x32_bf16 v[106:109], v[192:195], v[162:165], v[106:109]
	global_load_lds_dwordx4 v179, s[36:37]
	v_mfma_f32_16x16x32_bf16 v[102:105], v[192:195], v[166:169], v[102:105]
	s_add_u32 s36, s36, 0x20000
	s_addc_u32 s37, s37, 0
	s_addk_i32 m0, 0x2000
	v_mfma_f32_16x16x32_bf16 v[98:101], v[192:195], v[170:173], v[98:101]
	s_waitcnt lgkmcnt(2)
	v_mfma_f32_16x16x32_bf16 v[94:97], v[196:199], v[158:161], v[94:97]
	ds_read_b128 v[192:195], v157 offset:10240
	v_mfma_f32_16x16x32_bf16 v[90:93], v[196:199], v[162:165], v[90:93]
	global_load_lds_dwordx4 v179, s[36:37]
	v_mfma_f32_16x16x32_bf16 v[86:89], v[196:199], v[166:169], v[86:89]
	s_add_u32 s36, s36, 0x20000
	s_addc_u32 s37, s37, 0
	s_addk_i32 m0, 0x2000
	v_mfma_f32_16x16x32_bf16 v[82:85], v[196:199], v[170:173], v[82:85]
	s_waitcnt lgkmcnt(2)
	v_mfma_f32_16x16x32_bf16 v[78:81], v[200:203], v[158:161], v[78:81]
	ds_read_b128 v[196:199], v157 offset:12288
	v_mfma_f32_16x16x32_bf16 v[74:77], v[200:203], v[162:165], v[74:77]
	global_load_lds_dwordx4 v179, s[36:37]
	v_mfma_f32_16x16x32_bf16 v[70:73], v[200:203], v[166:169], v[70:73]
	s_add_u32 s36, s36, 0xfffa0080
	s_addc_u32 s37, s37, -1
	s_addk_i32 m0, 0x2000
	v_mfma_f32_16x16x32_bf16 v[66:69], v[200:203], v[170:173], v[66:69]
	s_waitcnt lgkmcnt(2)
	v_mfma_f32_16x16x32_bf16 v[62:65], v[174:177], v[158:161], v[62:65]
	ds_read_b128 v[200:203], v157 offset:14336
	v_mfma_f32_16x16x32_bf16 v[58:61], v[174:177], v[162:165], v[58:61]
	global_load_lds_dwordx4 v179, s[38:39]
	v_mfma_f32_16x16x32_bf16 v[54:57], v[174:177], v[166:169], v[54:57]
	s_add_u32 s38, s38, 0x20000
	s_addc_u32 s39, s39, 0
	s_addk_i32 m0, 0x2000
	v_mfma_f32_16x16x32_bf16 v[50:53], v[174:177], v[170:173], v[50:53]
	ds_read_b128 v[174:177], v178 offset:33792
	ds_read_b128 v[204:207], v178 offset:35840
	ds_read_b128 v[208:211], v178 offset:37888
	ds_read_b128 v[212:215], v178 offset:39936
	ds_read_b128 v[216:219], v157 offset:1024
	s_waitcnt lgkmcnt(7)
	v_mfma_f32_16x16x32_bf16 v[46:49], v[192:195], v[158:161], v[46:49]
	v_mfma_f32_16x16x32_bf16 v[42:45], v[192:195], v[162:165], v[42:45]
	global_load_lds_dwordx4 v179, s[38:39]
	v_mfma_f32_16x16x32_bf16 v[38:41], v[192:195], v[166:169], v[38:41]
	s_add_u32 s38, s38, 0x20000
	s_addc_u32 s39, s39, 0
	s_addk_i32 m0, 0x2000
	v_mfma_f32_16x16x32_bf16 v[34:37], v[192:195], v[170:173], v[34:37]
	s_waitcnt lgkmcnt(6)
	v_mfma_f32_16x16x32_bf16 v[30:33], v[196:199], v[158:161], v[30:33]
	ds_read_b128 v[192:195], v157 offset:3072
	v_mfma_f32_16x16x32_bf16 v[26:29], v[196:199], v[162:165], v[26:29]
	global_load_lds_dwordx4 v179, s[38:39]
	v_mfma_f32_16x16x32_bf16 v[22:25], v[196:199], v[166:169], v[22:25]
	s_add_u32 s38, s38, 0x20000
	s_addc_u32 s39, s39, 0
	s_addk_i32 m0, 0x2000
	v_mfma_f32_16x16x32_bf16 v[18:21], v[196:199], v[170:173], v[18:21]
	s_waitcnt lgkmcnt(6)
	v_mfma_f32_16x16x32_bf16 v[14:17], v[200:203], v[158:161], v[14:17]
	ds_read_b128 v[158:161], v157 offset:5120
	v_mfma_f32_16x16x32_bf16 v[10:13], v[200:203], v[162:165], v[10:13]
	global_load_lds_dwordx4 v179, s[38:39]
	v_mfma_f32_16x16x32_bf16 v[6:9], v[200:203], v[166:169], v[6:9]
	s_add_u32 s38, s38, 0xfffa0080
	s_addc_u32 s39, s39, -1
	v_mfma_f32_16x16x32_bf16 v[2:5], v[200:203], v[170:173], v[2:5]
	s_waitcnt lgkmcnt(2)
	v_mfma_f32_16x16x32_bf16 v[126:129], v[216:219], v[174:177], v[126:129]
	ds_read_b128 v[162:165], v157 offset:7168
	v_mfma_f32_16x16x32_bf16 v[122:125], v[216:219], v[204:207], v[122:125]
	v_mfma_f32_16x16x32_bf16 v[118:121], v[216:219], v[208:211], v[118:121]
	v_mfma_f32_16x16x32_bf16 v[114:117], v[216:219], v[212:215], v[114:117]
	s_waitcnt lgkmcnt(2)
	v_mfma_f32_16x16x32_bf16 v[110:113], v[192:195], v[174:177], v[110:113]
	ds_read_b128 v[166:169], v157 offset:9216
	v_mfma_f32_16x16x32_bf16 v[106:109], v[192:195], v[204:207], v[106:109]
	v_mfma_f32_16x16x32_bf16 v[102:105], v[192:195], v[208:211], v[102:105]
	v_mfma_f32_16x16x32_bf16 v[98:101], v[192:195], v[212:215], v[98:101]
	s_waitcnt lgkmcnt(2)
	v_mfma_f32_16x16x32_bf16 v[94:97], v[158:161], v[174:177], v[94:97]
	ds_read_b128 v[170:173], v157 offset:11264
	v_mfma_f32_16x16x32_bf16 v[90:93], v[158:161], v[204:207], v[90:93]
	v_mfma_f32_16x16x32_bf16 v[86:89], v[158:161], v[208:211], v[86:89]
	v_mfma_f32_16x16x32_bf16 v[82:85], v[158:161], v[212:215], v[82:85]
	s_waitcnt lgkmcnt(2)
; #define WAIT_V0() asm volatile("s_waitcnt vmcnt(0)" ::: "memory")
; template <int MF, int NF>
; __device__ __forceinline__ void gemm_main(int zz, f32x4 (&acc)[MF][NF], const u16* __restrict__ Wt, int ldw,
;                                           const u16* __restrict__ Act, int lda, int K, char* shm) {
;     ...
;   for (int t = 0; t < nt; ++t) {
;     const int cur = t & 1;
;     if (t + 1 < nt) {
; #pragma unroll
;       for (int i = 0; i < NLD; ++i) {
;         const u16* src = (i < NLA) ? (Wt + (long)(i * 64) * ldw + (t + 1) * 64 + voffA)
;                                    : (Act + (long)((i - NLA) * 64) * lda + (t + 1) * 64 + voffB);
;         __builtin_amdgcn_global_load_lds((const unsigned*)src, (unsigned*)(shm + (cur ^ 1) * STAGE_B + (i * 8 + wid) * 1024), 16, 0, 0);
;       }
;     }
;     const char* sbase = shm + cur * STAGE_B;
;     {
;       constexpr int D = (NF >= 4) ? 3 : ((MF >= 12) ? 6 : 4), RING = D + 1, NSTEP = 2 * MF;
;       bf16x8 Bf[2][NF], Ar[RING];
; #pragma unroll
;       for (int n = 0; n < NF; ++n) Bf[0][n] = *(const bf16x8*)(sbase + boff + (n * 2 + 0) * 1024);
; #pragma unroll
;       for (int j = 0; j < D; ++j) Ar[j % RING] = *(const bf16x8*)(sbase + aoff + ((j % MF) * 2 + (j / MF)) * 1024);
;       __builtin_amdgcn_sched_barrier(0);
;       __builtin_amdgcn_s_setprio(1);
; #pragma unroll
;       for (int i = 0; i < NSTEP; ++i) {
;         const int ks = i / MF, m = i % MF;
;         const int j = i + D;
;         if (j < NSTEP) {
;           const int ksj = j / MF, mj = j % MF;
;           if (mj == 0) {
; #pragma unroll
;             for (int n = 0; n < NF; ++n) Bf[ksj][n] = *(const bf16x8*)(sbase + boff + (n * 2 + ksj) * 1024);
;           }
;           Ar[j % RING] = *(const bf16x8*)(sbase + aoff + (mj * 2 + ksj) * 1024);
;         }
; #pragma unroll
;         for (int n = 0; n < NF; ++n) acc[m][n] = __builtin_amdgcn_mfma_f32_16x16x32_bf16(Ar[i % RING], Bf[ks][n], acc[m][n], 0, 0, 0);
;         __builtin_amdgcn_sched_barrier(0);
;       }
;       __builtin_amdgcn_s_setprio(0);
;     }
;     WAIT_V0();
;     __syncthreads();
	v_mfma_f32_16x16x32_bf16 v[78:81], v[162:165], v[174:177], v[78:81]
	ds_read_b128 v[158:161], v157 offset:13312
	v_mfma_f32_16x16x32_bf16 v[74:77], v[162:165], v[204:207], v[74:77]
	v_mfma_f32_16x16x32_bf16 v[70:73], v[162:165], v[208:211], v[70:73]
	v_mfma_f32_16x16x32_bf16 v[66:69], v[162:165], v[212:215], v[66:69]
	s_waitcnt lgkmcnt(2)
	v_mfma_f32_16x16x32_bf16 v[62:65], v[166:169], v[174:177], v[62:65]
	ds_read_b128 v[162:165], v157 offset:15360
	v_mfma_f32_16x16x32_bf16 v[58:61], v[166:169], v[204:207], v[58:61]
	v_mfma_f32_16x16x32_bf16 v[54:57], v[166:169], v[208:211], v[54:57]
	v_mfma_f32_16x16x32_bf16 v[50:53], v[166:169], v[212:215], v[50:53]
	s_waitcnt lgkmcnt(2)
	v_mfma_f32_16x16x32_bf16 v[46:49], v[170:173], v[174:177], v[46:49]
	v_mfma_f32_16x16x32_bf16 v[42:45], v[170:173], v[204:207], v[42:45]
	v_mfma_f32_16x16x32_bf16 v[38:41], v[170:173], v[208:211], v[38:41]
	v_mfma_f32_16x16x32_bf16 v[34:37], v[170:173], v[212:215], v[34:37]
	s_waitcnt lgkmcnt(1)
	v_mfma_f32_16x16x32_bf16 v[30:33], v[158:161], v[174:177], v[30:33]
	v_mfma_f32_16x16x32_bf16 v[26:29], v[158:161], v[204:207], v[26:29]
	v_mfma_f32_16x16x32_bf16 v[22:25], v[158:161], v[208:211], v[22:25]
	v_mfma_f32_16x16x32_bf16 v[18:21], v[158:161], v[212:215], v[18:21]
	s_waitcnt lgkmcnt(0)
	v_mfma_f32_16x16x32_bf16 v[14:17], v[162:165], v[174:177], v[14:17]
	v_mfma_f32_16x16x32_bf16 v[10:13], v[162:165], v[204:207], v[10:13]
	v_mfma_f32_16x16x32_bf16 v[6:9], v[162:165], v[208:211], v[6:9]
	v_mfma_f32_16x16x32_bf16 v[2:5], v[162:165], v[212:215], v[2:5]
	s_nop 0
	s_add_i32 s3, s3, 0x10000
	s_waitcnt vmcnt(0)
	s_add_u32 s6, s6, 0x80
	s_addc_u32 s7, s7, 0
	s_cmpk_lg_i32 s6, 0x780
	s_waitcnt vmcnt(0)
	s_barrier
	s_cbranch_scc1 .LBB0_224
	ds_read_b128 v[140:143], v0 offset:2048
	ds_read_b128 v[158:161], v0
	ds_read_b128 v[162:165], v156 offset:38912
	ds_read_b128 v[166:169], v156 offset:36864
	ds_read_b128 v[170:173], v156 offset:34816
	ds_read_b128 v[174:177], v0 offset:4096
	ds_read_b128 v[192:195], v156 offset:32768
	s_setprio 1
	s_waitcnt lgkmcnt(3)
	v_mfma_f32_16x16x32_bf16 v[196:199], v[158:161], v[166:169], v[118:121]
	s_nop 2
	ds_read_b128 v[118:121], v0 offset:6144
	s_waitcnt lgkmcnt(1)
	v_mfma_f32_16x16x32_bf16 v[126:129], v[158:161], v[192:195], v[126:129]
	v_mfma_f32_16x16x32_bf16 v[122:125], v[158:161], v[170:173], v[122:125]
	v_mfma_f32_16x16x32_bf16 v[114:117], v[158:161], v[162:165], v[114:117]
	v_mfma_f32_16x16x32_bf16 v[110:113], v[140:143], v[192:195], v[110:113]
	ds_read_b128 v[158:161], v0 offset:8192
	v_mfma_f32_16x16x32_bf16 v[106:109], v[140:143], v[170:173], v[106:109]
	v_mfma_f32_16x16x32_bf16 v[102:105], v[140:143], v[166:169], v[102:105]
	v_mfma_f32_16x16x32_bf16 v[98:101], v[140:143], v[162:165], v[98:101]
	v_mfma_f32_16x16x32_bf16 v[140:143], v[174:177], v[166:169], v[86:89]
	s_nop 2
	ds_read_b128 v[86:89], v0 offset:10240
	v_mfma_f32_16x16x32_bf16 v[94:97], v[174:177], v[192:195], v[94:97]
	v_mfma_f32_16x16x32_bf16 v[90:93], v[174:177], v[170:173], v[90:93]
	v_mfma_f32_16x16x32_bf16 v[174:177], v[174:177], v[162:165], v[82:85]
	s_waitcnt lgkmcnt(2)
	v_mfma_f32_16x16x32_bf16 v[200:203], v[118:121], v[166:169], v[70:73]
	s_nop 2
	ds_read_b128 v[70:73], v0 offset:12288
	v_mfma_f32_16x16x32_bf16 v[78:81], v[118:121], v[192:195], v[78:81]
	v_mfma_f32_16x16x32_bf16 v[74:77], v[118:121], v[170:173], v[74:77]
	v_mfma_f32_16x16x32_bf16 v[204:207], v[118:121], v[162:165], v[66:69]
	s_waitcnt lgkmcnt(2)
	v_mfma_f32_16x16x32_bf16 v[208:211], v[158:161], v[166:169], v[54:57]
	s_nop 2
	ds_read_b128 v[54:57], v0 offset:14336
	v_mfma_f32_16x16x32_bf16 v[62:65], v[158:161], v[192:195], v[62:65]
	v_mfma_f32_16x16x32_bf16 v[58:61], v[158:161], v[170:173], v[58:61]
	v_mfma_f32_16x16x32_bf16 v[158:161], v[158:161], v[162:165], v[50:53]
	ds_read_b128 v[212:215], v156 offset:35840
	ds_read_b128 v[216:219], v156 offset:37888
	s_waitcnt lgkmcnt(4)
	v_mfma_f32_16x16x32_bf16 v[220:223], v[86:89], v[166:169], v[38:41]
	ds_read_b128 v[224:227], v156 offset:39936
	ds_read_b128 v[228:231], v156 offset:33792
	s_nop 0
	ds_read_b128 v[38:41], v0 offset:1024
	v_mfma_f32_16x16x32_bf16 v[46:49], v[86:89], v[192:195], v[46:49]
	v_mfma_f32_16x16x32_bf16 v[42:45], v[86:89], v[170:173], v[42:45]
	v_mfma_f32_16x16x32_bf16 v[232:235], v[86:89], v[162:165], v[34:37]
	s_waitcnt lgkmcnt(6)
	v_mfma_f32_16x16x32_bf16 v[240:243], v[70:73], v[170:173], v[26:29]
	s_nop 2
	ds_read_b128 v[26:29], v0 offset:3072
	v_mfma_f32_16x16x32_bf16 v[236:239], v[70:73], v[192:195], v[30:33]
	v_mfma_f32_16x16x32_bf16 v[244:247], v[70:73], v[166:169], v[22:25]
	v_mfma_f32_16x16x32_bf16 v[248:251], v[70:73], v[162:165], v[18:21]
	s_waitcnt lgkmcnt(6)
	v_mfma_f32_16x16x32_bf16 v[170:173], v[54:57], v[170:173], v[10:13]
	s_nop 2
	ds_read_b128 v[10:13], v0 offset:5120
	v_mfma_f32_16x16x32_bf16 v[6:9], v[54:57], v[166:169], v[6:9]
	v_mfma_f32_16x16x32_bf16 v[192:195], v[54:57], v[192:195], v[14:17]
	v_mfma_f32_16x16x32_bf16 v[162:165], v[54:57], v[162:165], v[2:5]
	s_nop 2
	ds_read_b128 v[2:5], v0 offset:7168
	s_waitcnt lgkmcnt(3)
; #define WAIT_V0() asm volatile("s_waitcnt vmcnt(0)" ::: "memory")
; template <int MF, int NF>
; __device__ __forceinline__ void gemm_main(int zz, f32x4 (&acc)[MF][NF], const u16* __restrict__ Wt, int ldw,
;                                           const u16* __restrict__ Act, int lda, int K, char* shm) {
;     ...
;       for (int i = 0; i < NSTEP; ++i) {
;         const int ks = i / MF, m = i % MF;
;         const int j = i + D;
;         if (j < NSTEP) {
;           const int ksj = j / MF, mj = j % MF;
;           if (mj == 0) {
; #pragma unroll
;             for (int n = 0; n < NF; ++n) Bf[ksj][n] = *(const bf16x8*)(sbase + boff + (n * 2 + ksj) * 1024);
;           }
;           Ar[j % RING] = *(const bf16x8*)(sbase + aoff + (mj * 2 + ksj) * 1024);
;         }
; #pragma unroll
;         for (int n = 0; n < NF; ++n) acc[m][n] = __builtin_amdgcn_mfma_f32_16x16x32_bf16(Ar[i % RING], Bf[ks][n], acc[m][n], 0, 0, 0);
;         __builtin_amdgcn_sched_barrier(0);
;       }
;       __builtin_amdgcn_s_setprio(0);
;     }
;     WAIT_V0();
;     __syncthreads();
; template <int EPI>
; __device__ __forceinline__ void gemm_phase(int zz, const u16* __restrict__ Wt, const u16* __restrict__ Act, int K, int lda, int nColTiles,
;                            u16* __restrict__ Out, int ldo, int nvalid, char* shm) {
;     ...
;   for (; tile < ntiles; tile += gridDim.x) {
;     int gidx = tile / (8 * nColTiles), rem = tile % (8 * nColTiles);
;     int pm = gidx * 8 + (rem & 7), pn = rem >> 3;
;     int t0 = pm * 256, c0 = pn * 256;
;     f32x4 acc[8][4];
; #pragma unroll
;     for (int m = 0; m < 8; ++m)
; #pragma unroll
;       for (int n = 0; n < 4; ++n) acc[m][n] = f32x4{0.f, 0.f, 0.f, 0.f};
;     gemm_main<8, 4>(zz, acc, Wt + (long)c0 * K, K, Act + (long)t0 * lda, lda, K, shm);
;     {
;       int nx = tile + gridDim.x;
;       if (nx < ntiles) {
;         int g2 = nx / (8 * nColTiles), r2 = nx % (8 * nColTiles);
;         int pm2 = g2 * 8 + (r2 & 7), pn2 = r2 >> 3;
;         gemm_issue_first<8, 4>(zz, Wt + (long)(pn2 * 256) * K, K, Act + (long)(pm2 * 256) * lda, lda, shm);
;       }
	v_mfma_f32_16x16x32_bf16 v[118:121], v[38:41], v[228:231], v[126:129]
	v_mfma_f32_16x16x32_bf16 v[86:89], v[38:41], v[212:215], v[122:125]
	v_mfma_f32_16x16x32_bf16 v[54:57], v[38:41], v[216:219], v[196:199]
	v_mfma_f32_16x16x32_bf16 v[22:25], v[38:41], v[224:227], v[114:117]
	ds_read_b128 v[14:17], v0 offset:9216
	s_waitcnt lgkmcnt(3)
	v_mfma_f32_16x16x32_bf16 v[114:117], v[26:29], v[228:231], v[110:113]
	v_mfma_f32_16x16x32_bf16 v[82:85], v[26:29], v[212:215], v[106:109]
	v_mfma_f32_16x16x32_bf16 v[50:53], v[26:29], v[216:219], v[102:105]
	v_mfma_f32_16x16x32_bf16 v[18:21], v[26:29], v[224:227], v[98:101]
	ds_read_b128 v[26:29], v0 offset:11264
	s_waitcnt lgkmcnt(3)
	v_mfma_f32_16x16x32_bf16 v[102:105], v[10:13], v[228:231], v[94:97]
	v_mfma_f32_16x16x32_bf16 v[70:73], v[10:13], v[212:215], v[90:93]
	v_mfma_f32_16x16x32_bf16 v[38:41], v[10:13], v[216:219], v[140:143]
	v_mfma_f32_16x16x32_bf16 v[10:13], v[10:13], v[224:227], v[174:177]
	s_waitcnt lgkmcnt(2)
	v_mfma_f32_16x16x32_bf16 v[66:69], v[2:5], v[212:215], v[74:77]
	s_nop 2
	ds_read_b128 v[74:77], v0 offset:13312
	v_mfma_f32_16x16x32_bf16 v[98:101], v[2:5], v[228:231], v[78:81]
	v_mfma_f32_16x16x32_bf16 v[34:37], v[2:5], v[216:219], v[200:203]
	v_mfma_f32_16x16x32_bf16 v[2:5], v[2:5], v[224:227], v[204:207]
	s_waitcnt lgkmcnt(2)
	v_mfma_f32_16x16x32_bf16 v[126:129], v[14:17], v[228:231], v[62:65]
	ds_read_b128 v[140:143], v0 offset:15360
	v_mfma_f32_16x16x32_bf16 v[94:97], v[14:17], v[212:215], v[58:61]
	v_mfma_f32_16x16x32_bf16 v[62:65], v[14:17], v[216:219], v[208:211]
	v_mfma_f32_16x16x32_bf16 v[30:33], v[14:17], v[224:227], v[158:161]
	s_waitcnt lgkmcnt(2)
	v_mfma_f32_16x16x32_bf16 v[122:125], v[26:29], v[228:231], v[46:49]
	v_mfma_f32_16x16x32_bf16 v[90:93], v[26:29], v[212:215], v[42:45]
	v_mfma_f32_16x16x32_bf16 v[58:61], v[26:29], v[216:219], v[220:223]
	v_mfma_f32_16x16x32_bf16 v[26:29], v[26:29], v[224:227], v[232:235]
	s_waitcnt lgkmcnt(1)
	v_mfma_f32_16x16x32_bf16 v[110:113], v[74:77], v[228:231], v[236:239]
	v_mfma_f32_16x16x32_bf16 v[78:81], v[74:77], v[212:215], v[240:243]
	v_mfma_f32_16x16x32_bf16 v[46:49], v[74:77], v[216:219], v[244:247]
	v_mfma_f32_16x16x32_bf16 v[14:17], v[74:77], v[224:227], v[248:251]
	s_waitcnt lgkmcnt(0)
	v_mfma_f32_16x16x32_bf16 v[106:109], v[140:143], v[228:231], v[192:195]
	v_mfma_f32_16x16x32_bf16 v[74:77], v[140:143], v[212:215], v[170:173]
	v_mfma_f32_16x16x32_bf16 v[42:45], v[140:143], v[216:219], v[6:9]
	v_mfma_f32_16x16x32_bf16 v[6:9], v[140:143], v[224:227], v[162:165]
	s_setprio 0
	s_add_i32 s15, s15, s14
	s_waitcnt vmcnt(0)
	s_cmpk_gt_i32 s15, 0xaff
	s_cselect_b64 s[6:7], -1, 0
	s_and_b64 vcc, exec, s[6:7]
	s_barrier
	s_cbranch_vccnz .LBB0_222
	s_mul_hi_i32 s3, s15, 0x2e8ba2e9
	s_lshr_b32 s5, s3, 31
	s_ashr_i32 s3, s3, 5
	s_add_i32 s3, s3, s5
	s_mul_i32 s5, s3, 0xb0
	s_sub_i32 s5, s15, s5
	s_lshl_b32 s8, s5, 5
	s_lshl_b32 s5, s5, 8
	s_and_b32 s8, s8, 0xffffff00
	s_lshl_b32 s3, s3, 11
	s_and_b32 s5, s5, 0x700
	s_ashr_i32 s9, s8, 31
	s_or_b32 s10, s5, s3
	s_lshl_b64 s[8:9], s[8:9], 11
	s_ashr_i32 s11, s10, 31
	v_readfirstlane_b32 s3, v131
	s_lshl_b64 s[10:11], s[10:11], 11
	v_lshl_add_u64 v[142:143], v[134:135], 0, s[8:9]
	s_mov_b32 m0, s3
	s_mov_b64 s[8:9], 0x20000
	v_readfirstlane_b32 s3, v144
	v_lshl_add_u64 v[140:141], v[132:133], 0, s[10:11]
	global_load_lds_dwordx4 v[142:143], off
	v_lshl_add_u64 v[158:159], v[142:143], 0, s[8:9]
	s_mov_b32 m0, s3
	s_mov_b64 s[10:11], 0x40000
	v_readfirstlane_b32 s3, v145
	global_load_lds_dwordx4 v[158:159], off
	v_lshl_add_u64 v[158:159], v[142:143], 0, s[10:11]
	s_mov_b32 m0, s3
	s_mov_b64 s[12:13], 0x60000
	v_readfirstlane_b32 s3, v146
	global_load_lds_dwordx4 v[158:159], off
	v_lshl_add_u64 v[142:143], v[142:143], 0, s[12:13]
	s_mov_b32 m0, s3
	v_readfirstlane_b32 s3, v147
	global_load_lds_dwordx4 v[142:143], off
	s_mov_b32 m0, s3
	v_readfirstlane_b32 s3, v148
	global_load_lds_dwordx4 v[140:141], off
	v_lshl_add_u64 v[142:143], v[140:141], 0, s[8:9]
	s_mov_b32 m0, s3
	v_readfirstlane_b32 s3, v149
	global_load_lds_dwordx4 v[142:143], off
	v_lshl_add_u64 v[142:143], v[140:141], 0, s[10:11]
	s_mov_b32 m0, s3
	v_readfirstlane_b32 s3, v150
	global_load_lds_dwordx4 v[142:143], off
	v_lshl_add_u64 v[140:141], v[140:141], 0, s[12:13]
	s_mov_b32 m0, s3
	s_nop 0
	global_load_lds_dwordx4 v[140:141], off
	s_branch .LBB0_222
.LBB0_227:
	v_readlane_b32 s36, v254, 12
	v_readlane_b32 s37, v254, 13
	v_readlane_b32 s38, v254, 14
	v_readlane_b32 s39, v254, 15
	v_readlane_b32 s40, v254, 16
	v_readlane_b32 s41, v254, 17
	v_readlane_b32 s42, v254, 18
	s_setprio 0
	v_readlane_b32 s4, v253, 32
	s_cmp_lt_i32 s4, 5
	s_mov_b64 s[2:3], -1
	s_cbranch_scc1 .LBB0_231
	s_cmp_gt_i32 s4, 5
	s_mov_b64 s[24:25], -1
	s_cbranch_scc0 .LBB0_230
	v_readlane_b32 s2, v253, 32
	s_cmp_eq_u32 s2, 6
	s_mov_b64 s[24:25], 0
	s_cselect_b64 s[22:23], -1, 0

; template <int MF, int NF>
; __device__ __forceinline__ void gemm_issue_first(int zz, const u16* __restrict__ Wt, int ldw, const u16* __restrict__ Act, int lda,
;                                                  char* shm) {
;     ...
;   const int tid = TIDX, wid = tid >> 6, lane = tid & 63;
;   const int sb = lane * 16;
;   const int swz = sb ^ (((sb >> 9) & 1) << 5);
;   const int rr = swz >> 6, cc = (swz & 63) >> 1;
;   const unsigned voffA = (unsigned)(((wid >> 1) * 16 + rr) * ldw + (wid & 1) * 32 + cc);
;   const unsigned voffB = (unsigned)(((wid >> 1) * 16 + rr) * lda + (wid & 1) * 32 + cc);
; #pragma unroll
;   for (int i = 0; i < NLD; ++i) {
;     const u16* src = (i < NLA) ? (Wt + (long)(i * 64) * ldw + voffA) : (Act + (long)((i - NLA) * 64) * lda + voffB);
;     __builtin_amdgcn_global_load_lds((const unsigned*)src, (unsigned*)(shm + (i * 8 + wid) * 1024), 16, 0, 0);
;   }
; template <int EPI>
; __device__ __forceinline__ void gemm_phase(int zz, const u16* __restrict__ Wt, const u16* __restrict__ Act, int K, int lda, int nColTiles,
;                            u16* __restrict__ Out, int ldo, int nvalid, char* shm) {
;     ...
;   const int ntiles = nT * nColTiles;
;   int tile = virt_id();
;   __syncthreads();
;   if (tile < ntiles) {
;     int gidx = tile / (8 * nColTiles), rem = tile % (8 * nColTiles);
;     int pm = gidx * 8 + (rem & 7), pn = rem >> 3;
;     gemm_issue_first<8, 4>(zz, Wt + (long)(pn * 256) * K, K, Act + (long)(pm * 256) * lda, lda, shm);
;   }
.LBB0_250:
	v_writelane_b32 v254, s44, 19
	s_lshl_b32 s34, s8, 7
	s_cmp_ge_i32 s31, s34
	s_waitcnt vmcnt(0)
	s_barrier
	s_cbranch_scc1 .LBB0_260
	s_lshl_b32 s35, s8, 3
	v_cvt_f32_ubyte0_e32 v0, s35
	v_rcp_iflag_f32_e32 v0, v0
	s_sub_i32 s8, 0, s35
	s_abs_i32 s3, s31
	v_readlane_b32 s2, v253, 30
	v_mul_f32_e32 v0, 0x4f7ffffe, v0
	v_cvt_u32_f32_e32 v0, v0
	v_add_u32_e32 v10, s2, v180
	s_ashr_i32 s2, s31, 31
	v_and_b32_e32 v2, 32, v10
	v_readfirstlane_b32 s9, v0
	s_mul_i32 s8, s8, s9
	s_mul_hi_u32 s8, s9, s8
	s_add_i32 s36, s9, s8
	s_mul_hi_u32 s8, s3, s36
	s_mul_i32 s9, s8, s35
	s_sub_i32 s3, s3, s9
	s_add_i32 s10, s8, 1
	s_sub_i32 s9, s3, s35
	s_cmp_ge_u32 s3, s35
	s_cselect_b32 s8, s10, s8
	s_cselect_b32 s3, s9, s3
	s_add_i32 s9, s8, 1
	s_cmp_ge_u32 s3, s35
	s_cselect_b32 s3, s9, s8
	s_xor_b32 s3, s3, s2
	s_sub_i32 s8, s3, s2
	s_mul_i32 s2, s8, s35
	s_sub_i32 s9, s31, s2
	s_lshl_b32 s2, s9, 5
	s_and_b32 s2, s2, 0xffffff00
	s_mul_hi_i32 s3, s2, s29
	s_mul_i32 s2, s2, s29
	s_lshl_b64 s[2:3], s[2:3], 1
	v_lshlrev_b32_e32 v0, 4, v10
	s_add_u32 s2, s6, s2
	v_bitop3_b32 v0, v0, v2, 48 bitop3:0x6c
	s_addc_u32 s3, s7, s3
	s_lshl_b32 s9, s9, 8
	v_lshrrev_b32_e32 v3, 2, v10
	v_lshrrev_b32_e32 v12, 1, v0
	v_ashrrev_i32_e32 v0, 3, v10
	s_lshl_b32 s8, s8, 11
	s_and_b32 s9, s9, 0x700
	v_ashrrev_i32_e32 v11, 6, v10
	v_bfi_b32 v0, 15, v3, v0
	s_or_b32 s8, s9, s8
	v_mul_lo_u32 v13, s29, v0
	v_lshlrev_b32_e32 v0, 5, v11
	s_mul_hi_i32 s9, s8, s29
	s_mul_i32 s8, s8, s29
	v_and_b32_e32 v14, 32, v0
	s_lshl_b64 s[8:9], s[8:9], 1
	v_or3_b32 v0, v13, v12, v14
	s_add_u32 s8, s4, s8
	v_lshlrev_b32_e32 v131, 10, v11
	v_lshlrev_b64 v[2:3], 1, v[0:1]
	s_addc_u32 s9, s5, s9
	v_lshl_add_u64 v[6:7], s[2:3], 0, v[2:3]
	v_readfirstlane_b32 s2, v131
	v_readfirstlane_b32 s44, v131
	s_cmp_ge_u32 s44, 0x1000
	s_cbranch_scc0 .Lprio_pl
	s_setprio 1
.Lprio_pl:
	v_add_u32_e32 v140, 0x2000, v131
	v_lshl_add_u64 v[4:5], s[8:9], 0, v[2:3]
	s_mov_b32 m0, s2
	s_lshl_b32 s2, s29, 7
	s_mov_b32 s3, s77
	v_readfirstlane_b32 s8, v140
	v_add_u32_e32 v141, 0x4000, v131
	global_load_lds_dwordx4 v[6:7], off
	v_lshl_add_u64 v[8:9], v[6:7], 0, s[2:3]
	s_mov_b32 m0, s8
	v_readfirstlane_b32 s8, v141
	global_load_lds_dwordx4 v[8:9], off
	s_lshl_b32 s76, s29, 8
	s_mov_b32 m0, s8
	s_mul_i32 s8, s29, 0xc0
	v_add_u32_e32 v142, 0x6000, v131
	v_lshl_add_u64 v[8:9], v[6:7], 0, s[76:77]
	s_lshl_b32 s76, s8, 1
	v_readfirstlane_b32 s9, v142
	v_add_u32_e32 v143, 0x8000, v131
	global_load_lds_dwordx4 v[8:9], off
	v_lshl_add_u64 v[6:7], v[6:7], 0, s[76:77]
	s_mov_b32 m0, s9
	v_readfirstlane_b32 s9, v143
	v_add_u32_e32 v144, 0xa000, v131
	global_load_lds_dwordx4 v[6:7], off
	s_mov_b32 m0, s9
	v_readfirstlane_b32 s9, v144
	v_add_u32_e32 v145, 0xc000, v131
	global_load_lds_dwordx4 v[4:5], off
	v_lshl_add_u64 v[4:5], v[4:5], 0, s[2:3]
	s_mov_b32 m0, s9
	v_readfirstlane_b32 s9, v145
	v_add_u32_e32 v146, 0xe000, v131
	global_load_lds_dwordx4 v[4:5], off
	v_lshl_add_u64 v[4:5], v[4:5], 0, s[2:3]
	s_mov_b32 m0, s9
	v_readfirstlane_b32 s9, v146
	global_load_lds_dwordx4 v[4:5], off
	v_lshl_add_u64 v[4:5], v[4:5], 0, s[2:3]
	s_mov_b32 m0, s9
	s_lshr_b32 s37, s29, 6
	global_load_lds_dwordx4 v[4:5], off
	s_lshl_b32 s9, s29, 6
	v_lshlrev_b32_e32 v4, 6, v10
	v_lshlrev_b32_e32 v6, 2, v10
	s_add_i32 s37, s37, -1
	v_and_b32_e32 v0, 48, v10
	v_and_b32_e32 v5, 0x3c0, v4
	v_and_b32_e32 v6, 32, v6
	s_add_u32 s38, s6, 0x80
	v_bitop3_b32 v147, v5, v6, v0 bitop3:0x36
	v_lshlrev_b32_e32 v0, 13, v11
	v_lshl_add_u64 v[132:133], s[4:5], 0, v[2:3]
	v_lshl_add_u64 v[134:135], s[6:7], 0, v[2:3]
	v_lshlrev_b32_e32 v2, 1, v10
	s_addc_u32 s39, s7, 0
	s_lshl_b32 s40, s29, 1
	v_and_b32_e32 v149, 0x6000, v0
	v_ashrrev_i32_e32 v0, 1, v10
	v_and_b32_e32 v2, 0x60, v2
	s_movk_i32 s10, 0xff80
	s_add_u32 s41, s4, 0x80
	v_and_or_b32 v150, v0, s10, v2
	v_add3_u32 v0, v12, v13, v14
	s_addc_u32 s42, s5, 0
	s_lshl_b32 s76, s9, 1
	s_mov_b32 s80, s20
	v_and_b32_e32 v148, 0xffffc000, v4
	v_and_b32_e32 v151, 0xcf, v10
	v_lshlrev_b64 v[136:137], 1, v[0:1]
	s_mov_b64 s[78:79], s[76:77]
	s_lshl_b32 s4, s2, 1
	s_lshl_b32 s6, s8, 1
	s_branch .LBB0_253

; template <int MF, int NF>
; __device__ __forceinline__ void gemm_main(int zz, f32x4 (&acc)[MF][NF], const u16* __restrict__ Wt, int ldw,
;                                           const u16* __restrict__ Act, int lda, int K, char* shm) {
;     ...
;   for (int t = 0; t < nt; ++t) {
;     const int cur = t & 1;
;     if (t + 1 < nt) {
; #pragma unroll
;       for (int i = 0; i < NLD; ++i) {
;         const u16* src = (i < NLA) ? (Wt + (long)(i * 64) * ldw + (t + 1) * 64 + voffA)
;                                    : (Act + (long)((i - NLA) * 64) * lda + (t + 1) * 64 + voffB);
;         __builtin_amdgcn_global_load_lds((const unsigned*)src, (unsigned*)(shm + (cur ^ 1) * STAGE_B + (i * 8 + wid) * 1024), 16, 0, 0);
;       }
;     }
;     const char* sbase = shm + cur * STAGE_B;
;     {
;       constexpr int D = (NF >= 4) ? 3 : ((MF >= 12) ? 6 : 4), RING = D + 1, NSTEP = 2 * MF;
;       bf16x8 Bf[2][NF], Ar[RING];
; #pragma unroll
;       for (int n = 0; n < NF; ++n) Bf[0][n] = *(const bf16x8*)(sbase + boff + (n * 2 + 0) * 1024);
; #pragma unroll
;       for (int j = 0; j < D; ++j) Ar[j % RING] = *(const bf16x8*)(sbase + aoff + ((j % MF) * 2 + (j / MF)) * 1024);
;       __builtin_amdgcn_sched_barrier(0);
;       __builtin_amdgcn_s_setprio(1);
; #pragma unroll
;       for (int i = 0; i < NSTEP; ++i) {
;         const int ks = i / MF, m = i % MF;
;         const int j = i + D;
;         if (j < NSTEP) {
;           const int ksj = j / MF, mj = j % MF;
;           if (mj == 0) {
; #pragma unroll
;             for (int n = 0; n < NF; ++n) Bf[ksj][n] = *(const bf16x8*)(sbase + boff + (n * 2 + ksj) * 1024);
;           }
;           Ar[j % RING] = *(const bf16x8*)(sbase + aoff + (mj * 2 + ksj) * 1024);
;         }
; #pragma unroll
;         for (int n = 0; n < NF; ++n) acc[m][n] = __builtin_amdgcn_mfma_f32_16x16x32_bf16(Ar[i % RING], Bf[ks][n], acc[m][n], 0, 0, 0);
;         __builtin_amdgcn_sched_barrier(0);
;       }
.LBB0_254:
	s_and_b32 s8, s5, 0x10000
	s_xor_b32 s9, s8, 0x10000
	s_add_i32 s9, s9, s44
	s_mov_b32 m0, s9
	s_add_i32 s7, s7, 1
	v_or_b32_e32 v0, s8, v147
	v_add_u32_e32 v138, v0, v149
	v_add_u32_e32 v0, v0, v148
	ds_read_b128 v[168:171], v0
	ds_read_b128 v[152:155], v138 offset:32768
	ds_read_b128 v[156:159], v138 offset:34816
	ds_read_b128 v[160:163], v138 offset:36864
	ds_read_b128 v[164:167], v138 offset:38912
	ds_read_b128 v[172:175], v0 offset:2048
	ds_read_b128 v[176:179], v0 offset:4096
	s_nop 0
	s_waitcnt lgkmcnt(5)
	v_mfma_f32_16x16x32_bf16 v[126:129], v[168:171], v[152:155], v[126:129]
	ds_read_b128 v[192:195], v0 offset:6144
	s_waitcnt lgkmcnt(5)
	v_mfma_f32_16x16x32_bf16 v[122:125], v[168:171], v[156:159], v[122:125]
	global_load_lds_dwordx4 v136, s[12:13]
	s_waitcnt lgkmcnt(4)
	v_mfma_f32_16x16x32_bf16 v[118:121], v[168:171], v[160:163], v[118:121]
	s_addk_i32 m0, 0x2000
	s_waitcnt lgkmcnt(3)
	v_mfma_f32_16x16x32_bf16 v[114:117], v[168:171], v[164:167], v[114:117]
	s_waitcnt lgkmcnt(2)
	v_mfma_f32_16x16x32_bf16 v[110:113], v[172:175], v[152:155], v[110:113]
	ds_read_b128 v[168:171], v0 offset:8192
	v_mfma_f32_16x16x32_bf16 v[106:109], v[172:175], v[156:159], v[106:109]
	global_load_lds_dwordx4 v136, s[14:15]
	v_mfma_f32_16x16x32_bf16 v[102:105], v[172:175], v[160:163], v[102:105]
	s_addk_i32 m0, 0x2000
	v_mfma_f32_16x16x32_bf16 v[98:101], v[172:175], v[164:167], v[98:101]
	s_waitcnt lgkmcnt(2)
	v_mfma_f32_16x16x32_bf16 v[94:97], v[176:179], v[152:155], v[94:97]
	ds_read_b128 v[172:175], v0 offset:10240
	v_mfma_f32_16x16x32_bf16 v[90:93], v[176:179], v[156:159], v[90:93]
	global_load_lds_dwordx4 v136, s[16:17]
	v_mfma_f32_16x16x32_bf16 v[86:89], v[176:179], v[160:163], v[86:89]
	s_addk_i32 m0, 0x2000
	v_mfma_f32_16x16x32_bf16 v[82:85], v[176:179], v[164:167], v[82:85]
	s_waitcnt lgkmcnt(2)
	v_mfma_f32_16x16x32_bf16 v[78:81], v[192:195], v[152:155], v[78:81]
	ds_read_b128 v[176:179], v0 offset:12288
	v_mfma_f32_16x16x32_bf16 v[74:77], v[192:195], v[156:159], v[74:77]
	global_load_lds_dwordx4 v136, s[18:19]
	v_mfma_f32_16x16x32_bf16 v[70:73], v[192:195], v[160:163], v[70:73]
	s_addk_i32 m0, 0x2000
	v_mfma_f32_16x16x32_bf16 v[66:69], v[192:195], v[164:167], v[66:69]
	s_waitcnt lgkmcnt(2)
	v_mfma_f32_16x16x32_bf16 v[62:65], v[168:171], v[152:155], v[62:65]
	ds_read_b128 v[192:195], v0 offset:14336
	v_mfma_f32_16x16x32_bf16 v[58:61], v[168:171], v[156:159], v[58:61]
	global_load_lds_dwordx4 v136, s[20:21]
	v_mfma_f32_16x16x32_bf16 v[54:57], v[168:171], v[160:163], v[54:57]
	s_addk_i32 m0, 0x2000
	v_mfma_f32_16x16x32_bf16 v[50:53], v[168:171], v[164:167], v[50:53]
	ds_read_b128 v[168:171], v138 offset:33792
	ds_read_b128 v[196:199], v138 offset:35840
	ds_read_b128 v[200:203], v138 offset:37888
	ds_read_b128 v[204:207], v138 offset:39936
	ds_read_b128 v[208:211], v0 offset:1024
	s_waitcnt lgkmcnt(7)
	v_mfma_f32_16x16x32_bf16 v[46:49], v[172:175], v[152:155], v[46:49]
	v_mfma_f32_16x16x32_bf16 v[42:45], v[172:175], v[156:159], v[42:45]
	global_load_lds_dwordx4 v136, s[26:27]
	v_mfma_f32_16x16x32_bf16 v[38:41], v[172:175], v[160:163], v[38:41]
	s_addk_i32 m0, 0x2000
	v_mfma_f32_16x16x32_bf16 v[34:37], v[172:175], v[164:167], v[34:37]
	s_waitcnt lgkmcnt(6)
	v_mfma_f32_16x16x32_bf16 v[30:33], v[176:179], v[152:155], v[30:33]
	ds_read_b128 v[172:175], v0 offset:3072
	v_mfma_f32_16x16x32_bf16 v[26:29], v[176:179], v[156:159], v[26:29]
	global_load_lds_dwordx4 v136, s[22:23]
	v_mfma_f32_16x16x32_bf16 v[22:25], v[176:179], v[160:163], v[22:25]
	s_addk_i32 m0, 0x2000
	v_mfma_f32_16x16x32_bf16 v[18:21], v[176:179], v[164:167], v[18:21]
	s_waitcnt lgkmcnt(6)
	v_mfma_f32_16x16x32_bf16 v[14:17], v[192:195], v[152:155], v[14:17]
	ds_read_b128 v[152:155], v0 offset:5120
	v_mfma_f32_16x16x32_bf16 v[10:13], v[192:195], v[156:159], v[10:13]
	global_load_lds_dwordx4 v136, s[24:25]
	v_mfma_f32_16x16x32_bf16 v[6:9], v[192:195], v[160:163], v[6:9]
	v_mfma_f32_16x16x32_bf16 v[2:5], v[192:195], v[164:167], v[2:5]
	s_waitcnt lgkmcnt(2)
	v_mfma_f32_16x16x32_bf16 v[126:129], v[208:211], v[168:171], v[126:129]
	ds_read_b128 v[156:159], v0 offset:7168
	v_mfma_f32_16x16x32_bf16 v[122:125], v[208:211], v[196:199], v[122:125]
	v_mfma_f32_16x16x32_bf16 v[118:121], v[208:211], v[200:203], v[118:121]
	v_mfma_f32_16x16x32_bf16 v[114:117], v[208:211], v[204:207], v[114:117]
	s_waitcnt lgkmcnt(2)
	v_mfma_f32_16x16x32_bf16 v[110:113], v[172:175], v[168:171], v[110:113]
	ds_read_b128 v[160:163], v0 offset:9216
	v_mfma_f32_16x16x32_bf16 v[106:109], v[172:175], v[196:199], v[106:109]
	v_mfma_f32_16x16x32_bf16 v[102:105], v[172:175], v[200:203], v[102:105]
	v_mfma_f32_16x16x32_bf16 v[98:101], v[172:175], v[204:207], v[98:101]
	s_waitcnt lgkmcnt(2)
	v_mfma_f32_16x16x32_bf16 v[94:97], v[152:155], v[168:171], v[94:97]
	ds_read_b128 v[164:167], v0 offset:11264
	v_mfma_f32_16x16x32_bf16 v[90:93], v[152:155], v[196:199], v[90:93]
	v_mfma_f32_16x16x32_bf16 v[86:89], v[152:155], v[200:203], v[86:89]
	v_mfma_f32_16x16x32_bf16 v[82:85], v[152:155], v[204:207], v[82:85]
	s_waitcnt lgkmcnt(2)
	v_mfma_f32_16x16x32_bf16 v[78:81], v[156:159], v[168:171], v[78:81]
	ds_read_b128 v[152:155], v0 offset:13312
	v_mfma_f32_16x16x32_bf16 v[74:77], v[156:159], v[196:199], v[74:77]
	v_mfma_f32_16x16x32_bf16 v[70:73], v[156:159], v[200:203], v[70:73]
	v_mfma_f32_16x16x32_bf16 v[66:69], v[156:159], v[204:207], v[66:69]
	s_waitcnt lgkmcnt(2)
	v_mfma_f32_16x16x32_bf16 v[62:65], v[160:163], v[168:171], v[62:65]
	ds_read_b128 v[156:159], v0 offset:15360
	v_mfma_f32_16x16x32_bf16 v[58:61], v[160:163], v[196:199], v[58:61]
	v_mfma_f32_16x16x32_bf16 v[54:57], v[160:163], v[200:203], v[54:57]
	v_mfma_f32_16x16x32_bf16 v[50:53], v[160:163], v[204:207], v[50:53]
	s_waitcnt lgkmcnt(2)
; #define WAIT_V0() asm volatile("s_waitcnt vmcnt(0)" ::: "memory")
; template <int MF, int NF>
; __device__ __forceinline__ void gemm_main(int zz, f32x4 (&acc)[MF][NF], const u16* __restrict__ Wt, int ldw,
;                                           const u16* __restrict__ Act, int lda, int K, char* shm) {
;     ...
;   for (int t = 0; t < nt; ++t) {
;     const int cur = t & 1;
;     if (t + 1 < nt) {
; #pragma unroll
;       for (int i = 0; i < NLD; ++i) {
;         const u16* src = (i < NLA) ? (Wt + (long)(i * 64) * ldw + (t + 1) * 64 + voffA)
;                                    : (Act + (long)((i - NLA) * 64) * lda + (t + 1) * 64 + voffB);
;         __builtin_amdgcn_global_load_lds((const unsigned*)src, (unsigned*)(shm + (cur ^ 1) * STAGE_B + (i * 8 + wid) * 1024), 16, 0, 0);
;       }
;     }
;     const char* sbase = shm + cur * STAGE_B;
;     {
;       constexpr int D = (NF >= 4) ? 3 : ((MF >= 12) ? 6 : 4), RING = D + 1, NSTEP = 2 * MF;
;       bf16x8 Bf[2][NF], Ar[RING];
; #pragma unroll
;       for (int n = 0; n < NF; ++n) Bf[0][n] = *(const bf16x8*)(sbase + boff + (n * 2 + 0) * 1024);
; #pragma unroll
;       for (int j = 0; j < D; ++j) Ar[j % RING] = *(const bf16x8*)(sbase + aoff + ((j % MF) * 2 + (j / MF)) * 1024);
;       __builtin_amdgcn_sched_barrier(0);
;       __builtin_amdgcn_s_setprio(1);
; #pragma unroll
;       for (int i = 0; i < NSTEP; ++i) {
;         const int ks = i / MF, m = i % MF;
;         const int j = i + D;
;         if (j < NSTEP) {
;           const int ksj = j / MF, mj = j % MF;
;           if (mj == 0) {
; #pragma unroll
;             for (int n = 0; n < NF; ++n) Bf[ksj][n] = *(const bf16x8*)(sbase + boff + (n * 2 + ksj) * 1024);
;           }
;           Ar[j % RING] = *(const bf16x8*)(sbase + aoff + (mj * 2 + ksj) * 1024);
;         }
; #pragma unroll
;         for (int n = 0; n < NF; ++n) acc[m][n] = __builtin_amdgcn_mfma_f32_16x16x32_bf16(Ar[i % RING], Bf[ks][n], acc[m][n], 0, 0, 0);
;         __builtin_amdgcn_sched_barrier(0);
;       }
;       __builtin_amdgcn_s_setprio(0);
;     }
;     WAIT_V0();
;     __syncthreads();
	v_mfma_f32_16x16x32_bf16 v[46:49], v[164:167], v[168:171], v[46:49]
	v_mfma_f32_16x16x32_bf16 v[42:45], v[164:167], v[196:199], v[42:45]
	v_mfma_f32_16x16x32_bf16 v[38:41], v[164:167], v[200:203], v[38:41]
	v_mfma_f32_16x16x32_bf16 v[34:37], v[164:167], v[204:207], v[34:37]
	s_waitcnt lgkmcnt(1)
	v_mfma_f32_16x16x32_bf16 v[30:33], v[152:155], v[168:171], v[30:33]
	v_mfma_f32_16x16x32_bf16 v[26:29], v[152:155], v[196:199], v[26:29]
	v_mfma_f32_16x16x32_bf16 v[22:25], v[152:155], v[200:203], v[22:25]
	v_mfma_f32_16x16x32_bf16 v[18:21], v[152:155], v[204:207], v[18:21]
	s_waitcnt lgkmcnt(0)
	v_mfma_f32_16x16x32_bf16 v[14:17], v[156:159], v[168:171], v[14:17]
	v_mfma_f32_16x16x32_bf16 v[10:13], v[156:159], v[196:199], v[10:13]
	v_mfma_f32_16x16x32_bf16 v[6:9], v[156:159], v[200:203], v[6:9]
	v_mfma_f32_16x16x32_bf16 v[2:5], v[156:159], v[204:207], v[2:5]
	s_nop 0
	s_add_i32 s5, s5, 0x10000
	s_add_u32 s12, s12, 0x80
	s_addc_u32 s13, s13, 0
	s_add_u32 s14, s14, 0x80
	s_addc_u32 s15, s15, 0
	s_add_u32 s16, s16, 0x80
	s_addc_u32 s17, s17, 0
	s_add_u32 s18, s18, 0x80
	s_addc_u32 s19, s19, 0
	s_add_u32 s20, s20, 0x80
	s_addc_u32 s21, s21, 0
	s_add_u32 s22, s22, 0x80
	s_addc_u32 s23, s23, 0
	s_add_u32 s24, s24, 0x80
	s_addc_u32 s25, s25, 0
	s_waitcnt vmcnt(0)
	s_add_u32 s26, s26, 0x80
	s_addc_u32 s27, s27, 0
	s_cmp_lg_u32 s37, s7
	s_waitcnt vmcnt(0)
	s_barrier
	s_cbranch_scc1 .LBB0_254
	s_lshl_b32 s5, s37, 16
	s_and_b32 s5, s5, 0x10000
	v_or_b32_e32 v0, s5, v147
	v_add_u32_e32 v138, v0, v149
	ds_read_b128 v[152:155], v138 offset:32768
	ds_read_b128 v[156:159], v138 offset:34816
	ds_read_b128 v[160:163], v138 offset:36864
	ds_read_b128 v[164:167], v138 offset:38912
	v_add_u32_e32 v0, v0, v148
	ds_read_b128 v[168:171], v0
	ds_read_b128 v[172:175], v0 offset:2048
	ds_read_b128 v[176:179], v0 offset:4096
	s_setprio 1
	s_waitcnt lgkmcnt(2)
	v_mfma_f32_16x16x32_bf16 v[126:129], v[168:171], v[152:155], v[126:129]
	ds_read_b128 v[192:195], v0 offset:6144
	v_mfma_f32_16x16x32_bf16 v[122:125], v[168:171], v[156:159], v[122:125]
	v_mfma_f32_16x16x32_bf16 v[118:121], v[168:171], v[160:163], v[118:121]
	v_mfma_f32_16x16x32_bf16 v[114:117], v[168:171], v[164:167], v[114:117]
	s_waitcnt lgkmcnt(2)
	v_mfma_f32_16x16x32_bf16 v[168:171], v[172:175], v[160:163], v[102:105]
	s_nop 2
	ds_read_b128 v[102:105], v0 offset:8192
	v_mfma_f32_16x16x32_bf16 v[110:113], v[172:175], v[152:155], v[110:113]
	v_mfma_f32_16x16x32_bf16 v[106:109], v[172:175], v[156:159], v[106:109]
	v_mfma_f32_16x16x32_bf16 v[172:175], v[172:175], v[164:167], v[98:101]
	s_nop 2
	ds_read_b128 v[98:101], v0 offset:10240
	s_waitcnt lgkmcnt(3)
	v_mfma_f32_16x16x32_bf16 v[94:97], v[176:179], v[152:155], v[94:97]
	v_mfma_f32_16x16x32_bf16 v[90:93], v[176:179], v[156:159], v[90:93]
	v_mfma_f32_16x16x32_bf16 v[86:89], v[176:179], v[160:163], v[86:89]
	v_mfma_f32_16x16x32_bf16 v[82:85], v[176:179], v[164:167], v[82:85]
	s_waitcnt lgkmcnt(2)
	v_mfma_f32_16x16x32_bf16 v[196:199], v[192:195], v[160:163], v[70:73]
	s_nop 2
	ds_read_b128 v[70:73], v0 offset:12288
	v_mfma_f32_16x16x32_bf16 v[78:81], v[192:195], v[152:155], v[78:81]
	v_mfma_f32_16x16x32_bf16 v[176:179], v[192:195], v[156:159], v[74:77]
	v_mfma_f32_16x16x32_bf16 v[192:195], v[192:195], v[164:167], v[66:69]
	s_nop 2
	ds_read_b128 v[66:69], v0 offset:14336
	s_waitcnt lgkmcnt(3)
	v_mfma_f32_16x16x32_bf16 v[62:65], v[102:105], v[152:155], v[62:65]
	v_mfma_f32_16x16x32_bf16 v[58:61], v[102:105], v[156:159], v[58:61]
	v_mfma_f32_16x16x32_bf16 v[54:57], v[102:105], v[160:163], v[54:57]
	v_mfma_f32_16x16x32_bf16 v[200:203], v[102:105], v[164:167], v[50:53]
	ds_read_b128 v[212:215], v138 offset:33792
	ds_read_b128 v[216:219], v138 offset:35840
	s_waitcnt lgkmcnt(4)
	v_mfma_f32_16x16x32_bf16 v[220:223], v[98:101], v[160:163], v[38:41]
	ds_read_b128 v[224:227], v138 offset:37888
	ds_read_b128 v[228:231], v138 offset:39936
	s_nop 0
	ds_read_b128 v[38:41], v0 offset:1024
	v_mfma_f32_16x16x32_bf16 v[204:207], v[98:101], v[152:155], v[46:49]
	v_mfma_f32_16x16x32_bf16 v[208:211], v[98:101], v[156:159], v[42:45]
	v_mfma_f32_16x16x32_bf16 v[232:235], v[98:101], v[164:167], v[34:37]
	s_waitcnt lgkmcnt(6)
	v_mfma_f32_16x16x32_bf16 v[236:239], v[70:73], v[156:159], v[26:29]
	s_nop 2
	ds_read_b128 v[26:29], v0 offset:3072
	v_mfma_f32_16x16x32_bf16 v[30:33], v[70:73], v[152:155], v[30:33]
	v_mfma_f32_16x16x32_bf16 v[22:25], v[70:73], v[160:163], v[22:25]
	v_mfma_f32_16x16x32_bf16 v[240:243], v[70:73], v[164:167], v[18:21]
	s_waitcnt lgkmcnt(6)
	v_mfma_f32_16x16x32_bf16 v[156:159], v[66:69], v[156:159], v[10:13]
	s_nop 2
	ds_read_b128 v[10:13], v0 offset:5120
	v_mfma_f32_16x16x32_bf16 v[152:155], v[66:69], v[152:155], v[14:17]
	v_mfma_f32_16x16x32_bf16 v[160:163], v[66:69], v[160:163], v[6:9]
	v_mfma_f32_16x16x32_bf16 v[164:167], v[66:69], v[164:167], v[2:5]
	s_nop 0
	ds_read_b128 v[14:17], v0 offset:7168
	s_waitcnt lgkmcnt(3)
; #define WAIT_V0() asm volatile("s_waitcnt vmcnt(0)" ::: "memory")
; template <int MF, int NF>
; __device__ __forceinline__ void gemm_main(int zz, f32x4 (&acc)[MF][NF], const u16* __restrict__ Wt, int ldw,
;                                           const u16* __restrict__ Act, int lda, int K, char* shm) {
;     ...
;       for (int i = 0; i < NSTEP; ++i) {
;         const int ks = i / MF, m = i % MF;
;         const int j = i + D;
;         if (j < NSTEP) {
;           const int ksj = j / MF, mj = j % MF;
;           if (mj == 0) {
; #pragma unroll
;             for (int n = 0; n < NF; ++n) Bf[ksj][n] = *(const bf16x8*)(sbase + boff + (n * 2 + ksj) * 1024);
;           }
;           Ar[j % RING] = *(const bf16x8*)(sbase + aoff + (mj * 2 + ksj) * 1024);
;         }
; #pragma unroll
;         for (int n = 0; n < NF; ++n) acc[m][n] = __builtin_amdgcn_mfma_f32_16x16x32_bf16(Ar[i % RING], Bf[ks][n], acc[m][n], 0, 0, 0);
;         __builtin_amdgcn_sched_barrier(0);
;       }
;       __builtin_amdgcn_s_setprio(0);
;     }
;     WAIT_V0();
;     __syncthreads();
; template <int EPI>
; __device__ __forceinline__ void gemm_phase(int zz, const u16* __restrict__ Wt, const u16* __restrict__ Act, int K, int lda, int nColTiles,
;                            u16* __restrict__ Out, int ldo, int nvalid, char* shm) {
;     ...
;     {
;       int nx = tile + gridDim.x;
;       if (nx < ntiles) {
;         int g2 = nx / (8 * nColTiles), r2 = nx % (8 * nColTiles);
;         int pm2 = g2 * 8 + (r2 & 7), pn2 = r2 >> 3;
;         gemm_issue_first<8, 4>(zz, Wt + (long)(pn2 * 256) * K, K, Act + (long)(pm2 * 256) * lda, lda, shm);
;       }
;     }
; #pragma unroll
;     for (int n = 0; n < 4; ++n) {
;       int token = t0 + wc * 64 + n * 16 + fr;
;       if (EPI == 0) {
;         int col0 = c0 + wr * 128 + fq * 32;
;         if (col0 < nvalid) {
	v_mfma_f32_16x16x32_bf16 v[98:101], v[38:41], v[212:215], v[126:129]
	v_mfma_f32_16x16x32_bf16 v[66:69], v[38:41], v[216:219], v[122:125]
	v_mfma_f32_16x16x32_bf16 v[34:37], v[38:41], v[224:227], v[118:121]
	v_mfma_f32_16x16x32_bf16 v[2:5], v[38:41], v[228:231], v[114:117]
	ds_read_b128 v[18:21], v0 offset:9216
	s_waitcnt lgkmcnt(3)
	v_mfma_f32_16x16x32_bf16 v[102:105], v[26:29], v[212:215], v[110:113]
	v_mfma_f32_16x16x32_bf16 v[70:73], v[26:29], v[216:219], v[106:109]
	v_mfma_f32_16x16x32_bf16 v[38:41], v[26:29], v[224:227], v[168:171]
	v_mfma_f32_16x16x32_bf16 v[6:9], v[26:29], v[228:231], v[172:175]
	ds_read_b128 v[26:29], v0 offset:11264
	s_waitcnt lgkmcnt(3)
	v_mfma_f32_16x16x32_bf16 v[106:109], v[10:13], v[212:215], v[94:97]
	v_mfma_f32_16x16x32_bf16 v[74:77], v[10:13], v[216:219], v[90:93]
	v_mfma_f32_16x16x32_bf16 v[42:45], v[10:13], v[224:227], v[86:89]
	v_mfma_f32_16x16x32_bf16 v[10:13], v[10:13], v[228:231], v[82:85]
	ds_read_b128 v[94:97], v0 offset:13312
	s_waitcnt lgkmcnt(3)
	v_mfma_f32_16x16x32_bf16 v[110:113], v[14:17], v[212:215], v[78:81]
	v_mfma_f32_16x16x32_bf16 v[78:81], v[14:17], v[216:219], v[176:179]
	v_mfma_f32_16x16x32_bf16 v[46:49], v[14:17], v[224:227], v[196:199]
	v_mfma_f32_16x16x32_bf16 v[14:17], v[14:17], v[228:231], v[192:195]
	s_waitcnt lgkmcnt(2)
	v_mfma_f32_16x16x32_bf16 v[114:117], v[18:21], v[212:215], v[62:65]
	ds_read_b128 v[168:171], v0 offset:15360
	v_mfma_f32_16x16x32_bf16 v[82:85], v[18:21], v[216:219], v[58:61]
	v_mfma_f32_16x16x32_bf16 v[50:53], v[18:21], v[224:227], v[54:57]
	v_mfma_f32_16x16x32_bf16 v[18:21], v[18:21], v[228:231], v[200:203]
	s_waitcnt lgkmcnt(2)
	v_mfma_f32_16x16x32_bf16 v[122:125], v[26:29], v[212:215], v[204:207]
	v_mfma_f32_16x16x32_bf16 v[90:93], v[26:29], v[216:219], v[208:211]
	v_mfma_f32_16x16x32_bf16 v[58:61], v[26:29], v[224:227], v[220:223]
	v_mfma_f32_16x16x32_bf16 v[26:29], v[26:29], v[228:231], v[232:235]
	s_waitcnt lgkmcnt(1)
	v_mfma_f32_16x16x32_bf16 v[118:121], v[94:97], v[212:215], v[30:33]
	v_mfma_f32_16x16x32_bf16 v[86:89], v[94:97], v[216:219], v[236:239]
	v_mfma_f32_16x16x32_bf16 v[54:57], v[94:97], v[224:227], v[22:25]
	v_mfma_f32_16x16x32_bf16 v[22:25], v[94:97], v[228:231], v[240:243]
	s_waitcnt lgkmcnt(0)
	v_mfma_f32_16x16x32_bf16 v[126:129], v[168:171], v[212:215], v[152:155]
	v_mfma_f32_16x16x32_bf16 v[94:97], v[168:171], v[216:219], v[156:159]
	v_mfma_f32_16x16x32_bf16 v[62:65], v[168:171], v[224:227], v[160:163]
	v_mfma_f32_16x16x32_bf16 v[30:33], v[168:171], v[228:231], v[164:167]
	s_setprio 0
	s_add_i32 s31, s31, s30
	s_waitcnt vmcnt(0)
	s_cmp_ge_i32 s31, s34
	s_cselect_b64 s[12:13], -1, 0
	s_and_b64 vcc, exec, s[12:13]
	s_barrier
	s_cbranch_vccnz .LBB0_257
	s_abs_i32 s7, s31
	s_mul_hi_u32 s8, s7, s36
	s_mul_i32 s9, s8, s35
	s_sub_i32 s7, s7, s9
	s_ashr_i32 s5, s31, 31
	s_add_i32 s9, s8, 1
	s_sub_i32 s10, s7, s35
	s_cmp_ge_u32 s7, s35
	s_cselect_b32 s8, s9, s8
	s_cselect_b32 s7, s10, s7
	s_add_i32 s9, s8, 1
	s_cmp_ge_u32 s7, s35
	s_cselect_b32 s7, s9, s8
	s_xor_b32 s7, s7, s5
	s_sub_i32 s5, s7, s5
	s_mul_i32 s7, s5, s35
	s_sub_i32 s7, s31, s7
	s_lshl_b32 s8, s7, 5
	s_lshl_b32 s7, s7, 8
	s_lshl_b32 s5, s5, 11
	s_and_b32 s7, s7, 0x700
	s_and_b32 s8, s8, 0xffffff00
	s_or_b32 s5, s7, s5
	s_mul_hi_i32 s9, s8, s29
	s_mul_i32 s8, s8, s29
	s_mul_hi_i32 s11, s5, s29
	s_mul_i32 s10, s5, s29
	v_readfirstlane_b32 s5, v131
	v_lshl_add_u64 v[152:153], s[8:9], 1, v[134:135]
	s_mov_b32 m0, s5
	s_mov_b64 s[8:9], s[78:79]
	v_readfirstlane_b32 s5, v140
	global_load_lds_dwordx4 v[152:153], off
	v_lshl_add_u64 v[154:155], v[152:153], 0, s[8:9]
	s_mov_b32 m0, s5
	s_mov_b32 s5, s79
	global_load_lds_dwordx4 v[154:155], off
	v_lshl_add_u64 v[154:155], v[152:153], 0, s[4:5]
	v_readfirstlane_b32 s5, v141
	s_mov_b32 m0, s5
	s_mov_b32 s7, s79
	v_readfirstlane_b32 s5, v142
	global_load_lds_dwordx4 v[154:155], off
	v_lshl_add_u64 v[152:153], v[152:153], 0, s[6:7]
	s_mov_b32 m0, s5
	v_readfirstlane_b32 s5, v143
	v_lshl_add_u64 v[138:139], s[10:11], 1, v[132:133]
	global_load_lds_dwordx4 v[152:153], off
	s_mov_b32 m0, s5
	v_readfirstlane_b32 s5, v144
	global_load_lds_dwordx4 v[138:139], off
	v_lshl_add_u64 v[138:139], v[138:139], 0, s[2:3]
	s_mov_b32 m0, s5
	v_readfirstlane_b32 s5, v145
	global_load_lds_dwordx4 v[138:139], off
	v_lshl_add_u64 v[138:139], v[138:139], 0, s[2:3]
	s_mov_b32 m0, s5
	v_readfirstlane_b32 s5, v146
	global_load_lds_dwordx4 v[138:139], off
	v_lshl_add_u64 v[138:139], v[138:139], 0, s[2:3]
	s_mov_b32 m0, s5
	s_nop 0
	global_load_lds_dwordx4 v[138:139], off
	v_add_u32_e32 v138, s77, v150
	v_cmp_gt_i32_e32 vcc, s28, v138
	s_and_saveexec_b64 s[14:15], vcc
	s_cbranch_execz .LBB0_252
	s_branch .LBB0_258

; __device__ __forceinline__ void run_step(int zz, const Params& p, int s, char* shm) {
;     ...
;     gemm_phase<0>(zz, wt, act, K, K, nct, out, ldo, nvalid, shm);
;   }
;   if (kind == 5) mixer_phase(zz, p, l, j - 5, shm);
;   if (kind == 6) g4_phase(zz, p, shm);
.LBB0_260:
	v_readlane_b32 s44, v254, 19
	s_setprio 0
	v_readlane_b32 s0, v253, 32
	s_cmp_lt_i32 s0, 6
	s_mov_b64 s[0:1], -1
	s_mov_b64 s[22:23], s[82:83]
	s_mov_b64 s[24:25], s[84:85]
	s_cbranch_scc1 .LBB0_262
	v_readlane_b32 s2, v253, 32
	s_cmp_eq_u32 s2, 6
	s_mov_b64 s[0:1], 0
	s_cselect_b64 s[22:23], -1, 0

; __device__ __forceinline__ void sb_mfma(int zz, const Params& p, int bh, int qb, char* shm) {
;     ...
;     if (kbase <= tq0 + 31) {
;       const u16* ksb = Ks + cur * 64 * 72;
;       const u16* vsb = Vt + cur * 64 * 72;
;       f32x4 z[4][2];
; #pragma unroll
;       for (int m = 0; m < 4; ++m)
; #pragma unroll
;         for (int n = 0; n < 2; ++n) z[m][n] = f32x4{0.f, 0.f, 0.f, 0.f};
; #pragma unroll
;       for (int ds = 0; ds < 2; ++ds) {
;         bf16x8 kf[4];
; #pragma unroll
;         for (int m = 0; m < 4; ++m) kf[m] = *(const bf16x8*)(ksb + (m * 16 + fr) * 72 + ds * 32 + fq * 8);
; #pragma unroll
;         for (int m = 0; m < 4; ++m)
; #pragma unroll
;           for (int n = 0; n < 2; ++n) z[m][n] = __builtin_amdgcn_mfma_f32_16x16x32_bf16(kf[m], qf[n][ds], z[m][n], 0, 0, 0);
;       }
;       const bool diag = (kbase + 63 >= tq0);
;       bf16x8 pa[2][2];
; #pragma unroll
;       for (int n = 0; n < 2; ++n) {
;         const int tq = tq0 + n * 16 + fr;
;         const int key0 = kbase + fq * 16;
;         float L[16], X[16];
;         float T = 0.f;
; #pragma unroll
;         for (int m = 0; m < 4; ++m)
; #pragma unroll
;           for (int j = 0; j < 4; ++j) {
;             const int i = m * 4 + j;
;             float z2 = z[m][n][j] * cs;
;             float e = __builtin_amdgcn_exp2f(z2);
;             float l2 = __builtin_amdgcn_logf(1.0f + e);
;             l2 = (z2 > 60.f) ? z2 : l2;
;             float Lv = -l2;
;             if (diag) Lv = (key0 + i < tq) ? Lv : 0.f;
;             L[i] = Lv;
;             X[i] = z2 - l2;
;             T += Lv;
;           }
.LBB0_707:
	s_and_b32 s84, s6, 1
	s_sub_i32 s6, s83, 63
	v_cmp_le_i32_e32 vcc, s6, v113
	s_and_saveexec_b64 s[80:81], vcc
	s_cbranch_execz .LBB0_709
	v_readfirstlane_b32 s7, v100
	s_cmp_lt_i32 s83, s7
	s_cbranch_scc1 .Lsb_fast
	s_xor_b32 s85, s84, 1
	s_mulk_i32 s85, 0x2400
	v_or_b32_e32 v58, s85, v98
	v_add_u32_e32 v82, v58, v125
	ds_read_b128 v[58:61], v82
	ds_read_b128 v[62:65], v82 offset:2304
	ds_read_b128 v[66:69], v82 offset:4608
	ds_read_b128 v[70:73], v82 offset:6912
	v_and_b32_e32 v115, 64, v189
	s_waitcnt lgkmcnt(3)
	v_mfma_f32_16x16x32_bf16 v[74:77], v[58:61], v[2:5], 0
	v_add_u32_e32 v128, s83, v98
	v_cmp_lt_i32_e32 vcc, s83, v100
	s_waitcnt lgkmcnt(1)
	v_mfma_f32_16x16x32_bf16 v[116:119], v[66:69], v[2:5], 0
	v_mfma_f32_16x16x32_bf16 v[120:123], v[66:69], v[10:13], 0
	ds_read_b128 v[66:69], v82 offset:64
	ds_read_b128 v[148:151], v82 offset:2368
	ds_read_b128 v[152:155], v82 offset:4672
	ds_read_b128 v[156:159], v82 offset:6976
	v_mfma_f32_16x16x32_bf16 v[58:61], v[58:61], v[10:13], 0
	v_mfma_f32_16x16x32_bf16 v[78:81], v[62:65], v[2:5], 0
	v_mfma_f32_16x16x32_bf16 v[62:65], v[62:65], v[10:13], 0
	s_waitcnt lgkmcnt(3)
	v_mfma_f32_16x16x32_bf16 v[86:89], v[66:69], v[6:9], v[74:77]
	v_mfma_f32_16x16x32_bf16 v[140:143], v[70:73], v[2:5], 0
	v_mfma_f32_16x16x32_bf16 v[144:147], v[70:73], v[10:13], 0
	v_mfma_f32_16x16x32_bf16 v[70:73], v[66:69], v[14:17], v[58:61]
	s_waitcnt lgkmcnt(2)
	v_mfma_f32_16x16x32_bf16 v[66:69], v[148:151], v[14:17], v[62:65]
	s_waitcnt lgkmcnt(1)
	v_mfma_f32_16x16x32_bf16 v[62:65], v[152:155], v[14:17], v[120:123]
	s_nop 2
	v_mul_f32_e32 v122, 0x3e38aa3b, v86
	v_exp_f32_e32 v123, v122
	v_mfma_f32_16x16x32_bf16 v[82:85], v[148:151], v[6:9], v[78:81]
	v_add_u32_e32 v120, 64, v115
	v_subrev_u32_e32 v121, 63, v128
	v_add_f32_e32 v123, 1.0, v123
	v_mfma_f32_16x16x32_bf16 v[78:81], v[152:155], v[6:9], v[116:119]
	v_log_f32_e32 v123, v123
	s_nop 1
	v_or_b32_e32 v117, v115, v99
	v_lshlrev_b32_e32 v117, 2, v117
	v_xor_b32_e32 v119, 0x80, v117
	v_or_b32_e32 v117, v115, v108
	v_lshlrev_b32_e32 v118, 2, v117
	v_xor_b32_e32 v117, 16, v189
	v_cmp_lt_i32_e64 s[6:7], v117, v120
	v_or_b32_e32 v116, v115, v107
	s_waitcnt lgkmcnt(0)
	v_mfma_f32_16x16x32_bf16 v[74:77], v[156:159], v[6:9], v[140:143]
	v_cndmask_b32_e64 v115, v189, v117, s[6:7]
	v_xor_b32_e32 v117, 32, v189
	v_cmp_lt_i32_e64 s[6:7], v117, v120
	v_mfma_f32_16x16x32_bf16 v[58:61], v[156:159], v[14:17], v[144:147]
	v_subrev_u32_e32 v120, 55, v128
	v_cndmask_b32_e64 v117, v189, v117, s[6:7]
	v_cmp_lt_f32_e64 s[6:7], s99, v122
	v_lshlrev_b32_e32 v116, 2, v116
	v_lshlrev_b32_e32 v115, 2, v115
	v_cndmask_b32_e64 v122, v123, v122, s[6:7]
	v_cmp_lt_i32_e64 s[6:7], v121, v101
	s_or_b64 s[6:7], vcc, s[6:7]
	v_fma_f32 v131, v86, s98, -v122
	v_sub_f32_e32 v86, 0, v122
	v_cndmask_b32_e64 v122, 0, v86, s[6:7]
	v_mul_f32_e32 v86, 0x3e38aa3b, v87
	v_exp_f32_e32 v123, v86
	v_cmp_lt_f32_e64 s[8:9], s99, v86
	v_lshlrev_b32_e32 v117, 2, v117
	v_add_f32_e32 v123, 1.0, v123
	v_log_f32_e32 v123, v123
	s_nop 0
	v_cndmask_b32_e64 v123, v123, v86, s[8:9]
	v_subrev_u32_e32 v86, 62, v128
	v_cmp_lt_i32_e64 s[8:9], v86, v101
	s_or_b64 s[8:9], vcc, s[8:9]
	v_fma_f32 v133, v87, s98, -v123
	v_mul_f32_e32 v87, 0x3e38aa3b, v88
	v_cndmask_b32_e64 v132, 0, -v123, s[8:9]
	v_exp_f32_e32 v123, v87
	v_cmp_lt_f32_e64 s[10:11], s99, v87
	v_add_f32_e32 v122, v132, v122
	v_add_f32_e32 v123, 1.0, v123
	v_log_f32_e32 v123, v123
	s_nop 0
	v_cndmask_b32_e64 v123, v123, v87, s[10:11]
	v_subrev_u32_e32 v87, 61, v128
	v_cmp_lt_i32_e64 s[10:11], v87, v101
	s_or_b64 s[10:11], vcc, s[10:11]
	v_fma_f32 v136, v88, s98, -v123
	v_mul_f32_e32 v88, 0x3e38aa3b, v89
	v_cndmask_b32_e64 v134, 0, -v123, s[10:11]
	v_exp_f32_e32 v123, v88
	v_cmp_lt_f32_e64 s[12:13], s99, v88
	v_add_f32_e32 v122, v134, v122
	v_add_f32_e32 v123, 1.0, v123
	v_log_f32_e32 v123, v123
	s_nop 0
	v_cndmask_b32_e64 v123, v123, v88, s[12:13]
	v_subrev_u32_e32 v88, 60, v128
	v_cmp_lt_i32_e64 s[12:13], v88, v101
	s_or_b64 s[12:13], vcc, s[12:13]
	v_fma_f32 v138, v89, s98, -v123
	v_mul_f32_e32 v89, 0x3e38aa3b, v82
	v_cndmask_b32_e64 v137, 0, -v123, s[12:13]
	v_exp_f32_e32 v123, v89
	v_cmp_lt_f32_e64 s[14:15], s99, v89
	v_add_f32_e32 v122, v137, v122
	v_add_f32_e32 v123, 1.0, v123
	v_log_f32_e32 v123, v123
	s_nop 0
	v_cndmask_b32_e64 v123, v123, v89, s[14:15]
	v_subrev_u32_e32 v89, 59, v128
	v_cmp_lt_i32_e64 s[14:15], v89, v101
	s_or_b64 s[14:15], vcc, s[14:15]
	v_fma_f32 v141, v82, s98, -v123
	v_mul_f32_e32 v82, 0x3e38aa3b, v83
	v_cndmask_b32_e64 v140, 0, -v123, s[14:15]
	v_exp_f32_e32 v123, v82
	v_cmp_lt_f32_e64 s[16:17], s99, v82
	v_add_f32_e32 v122, v140, v122
	v_add_f32_e32 v123, 1.0, v123
	v_log_f32_e32 v123, v123
	s_nop 0
	v_cndmask_b32_e64 v123, v123, v82, s[16:17]
	v_subrev_u32_e32 v82, 58, v128
	v_cmp_lt_i32_e64 s[16:17], v82, v101
	s_or_b64 s[16:17], vcc, s[16:17]
	v_fma_f32 v143, v83, s98, -v123
	v_mul_f32_e32 v83, 0x3e38aa3b, v84
	v_cndmask_b32_e64 v142, 0, -v123, s[16:17]
	v_exp_f32_e32 v123, v83
	v_cmp_lt_f32_e64 s[18:19], s99, v83
	v_add_f32_e32 v122, v142, v122
	v_add_f32_e32 v123, 1.0, v123
	v_log_f32_e32 v123, v123
	s_nop 0
	v_cndmask_b32_e64 v123, v123, v83, s[18:19]
	v_subrev_u32_e32 v83, 57, v128
	v_cmp_lt_i32_e64 s[18:19], v83, v101
	s_or_b64 s[18:19], vcc, s[18:19]
	v_fma_f32 v145, v84, s98, -v123
	v_mul_f32_e32 v84, 0x3e38aa3b, v85
	v_cndmask_b32_e64 v144, 0, -v123, s[18:19]
	v_exp_f32_e32 v123, v84
	v_cmp_lt_f32_e64 s[20:21], s99, v84
	v_add_f32_e32 v122, v144, v122
	v_add_f32_e32 v123, 1.0, v123
	v_log_f32_e32 v123, v123
	s_nop 0
	v_cndmask_b32_e64 v123, v123, v84, s[20:21]
	v_subrev_u32_e32 v84, 56, v128
	v_cmp_lt_i32_e64 s[20:21], v84, v101
; __device__ __forceinline__ void sb_mfma(int zz, const Params& p, int bh, int qb, char* shm) {
;     ...
; #pragma unroll
;         for (int m = 0; m < 4; ++m)
; #pragma unroll
;           for (int j = 0; j < 4; ++j) {
;             const int i = m * 4 + j;
;             float z2 = z[m][n][j] * cs;
;             float e = __builtin_amdgcn_exp2f(z2);
;             float l2 = __builtin_amdgcn_logf(1.0f + e);
;             l2 = (z2 > 60.f) ? z2 : l2;
;             float Lv = -l2;
;             if (diag) Lv = (key0 + i < tq) ? Lv : 0.f;
;             L[i] = Lv;
;             X[i] = z2 - l2;
;             T += Lv;
;           }
;         float t1 = __shfl(T, lane + 16, 64), t2 = __shfl(T, lane + 32, 64), t3 = __shfl(T, lane + 48, 64);
;         float suf = ((fq < 3) ? t1 : 0.f) + ((fq < 2) ? t2 : 0.f) + ((fq < 1) ? t3 : 0.f);
;         float tot = T + __shfl_xor(T, 16, 64);
;         tot += __shfl_xor(tot, 32, 64);
;         float run = R[n] + suf;
;         float A[16];
; #pragma unroll
;         for (int i = 15; i >= 0; --i) {
;           float a = __builtin_amdgcn_exp2f(X[i] + run);
;           if (diag) a = (key0 + i < tq) ? a : 0.f;
;           A[i] = a;
;           run += L[i];
;         }
;         R[n] += tot;
; #pragma unroll
;         for (int kk = 0; kk < 2; ++kk) {
;           union { bf16x8 v; unsigned u[4]; } cv;
; #pragma unroll
;           for (int c = 0; c < 4; ++c) cv.u[c] = pack2(A[kk * 8 + 2 * c], A[kk * 8 + 2 * c + 1]);
;           pa[n][kk] = cv.v;
;         }
	s_or_b64 s[20:21], vcc, s[20:21]
	v_fma_f32 v147, v85, s98, -v123
	v_cndmask_b32_e64 v146, 0, -v123, s[20:21]
	v_add_f32_e32 v85, v146, v122
	v_mul_f32_e32 v122, 0x3e38aa3b, v78
	v_exp_f32_e32 v123, v122
	v_cmp_lt_f32_e64 s[22:23], s99, v122
	v_add_f32_e32 v123, 1.0, v123
	v_log_f32_e32 v123, v123
	s_nop 0
	v_cndmask_b32_e64 v122, v123, v122, s[22:23]
	v_cmp_lt_i32_e64 s[22:23], v120, v101
	s_or_b64 s[22:23], vcc, s[22:23]
	v_fma_f32 v78, v78, s98, -v122
	v_cndmask_b32_e64 v148, 0, -v122, s[22:23]
	v_add_f32_e32 v122, v148, v85
	v_mul_f32_e32 v85, 0x3e38aa3b, v79
	v_exp_f32_e32 v123, v85
	v_cmp_lt_f32_e64 s[24:25], s99, v85
	v_add_f32_e32 v123, 1.0, v123
	v_log_f32_e32 v123, v123
	s_nop 0
	v_cndmask_b32_e64 v123, v123, v85, s[24:25]
	v_subrev_u32_e32 v85, 54, v128
	v_cmp_lt_i32_e64 s[24:25], v85, v101
	s_or_b64 s[24:25], vcc, s[24:25]
	v_fma_f32 v79, v79, s98, -v123
	v_cndmask_b32_e64 v149, 0, -v123, s[24:25]
	v_add_f32_e32 v123, v149, v122
	v_mul_f32_e32 v122, 0x3e38aa3b, v80
	v_exp_f32_e32 v124, v122
	v_cmp_lt_f32_e64 s[26:27], s99, v122
	v_add_f32_e32 v124, 1.0, v124
	v_log_f32_e32 v124, v124
	s_nop 0
	v_cndmask_b32_e64 v124, v124, v122, s[26:27]
	v_subrev_u32_e32 v122, 53, v128
	v_cmp_lt_i32_e64 s[26:27], v122, v101
	s_or_b64 s[26:27], vcc, s[26:27]
	v_fma_f32 v80, v80, s98, -v124
	v_cndmask_b32_e64 v150, 0, -v124, s[26:27]
	v_add_f32_e32 v124, v150, v123
	v_mul_f32_e32 v123, 0x3e38aa3b, v81
	v_exp_f32_e32 v126, v123
	v_cmp_lt_f32_e64 s[28:29], s99, v123
	v_add_f32_e32 v126, 1.0, v126
	v_log_f32_e32 v126, v126
	s_nop 0
	v_cndmask_b32_e64 v126, v126, v123, s[28:29]
	v_subrev_u32_e32 v123, 52, v128
	v_cmp_lt_i32_e64 s[28:29], v123, v101
	s_or_b64 s[28:29], vcc, s[28:29]
	v_fma_f32 v81, v81, s98, -v126
	v_cndmask_b32_e64 v151, 0, -v126, s[28:29]
	v_mul_f32_e32 v126, 0x3e38aa3b, v74
	v_exp_f32_e32 v127, v126
	v_cmp_lt_f32_e64 s[30:31], s99, v126
	v_add_f32_e32 v124, v151, v124
	v_add_f32_e32 v127, 1.0, v127
	v_log_f32_e32 v127, v127
	s_nop 0
	v_cndmask_b32_e64 v126, v127, v126, s[30:31]
	v_subrev_u32_e32 v127, 51, v128
	v_cmp_lt_i32_e64 s[30:31], v127, v101
	s_or_b64 s[30:31], vcc, s[30:31]
	v_fma_f32 v74, v74, s98, -v126
	v_cndmask_b32_e64 v152, 0, -v126, s[30:31]
	v_add_f32_e32 v126, v152, v124
	v_mul_f32_e32 v124, 0x3e38aa3b, v75
	v_exp_f32_e32 v153, v124
	v_cmp_lt_f32_e64 s[34:35], s99, v124
	v_add_f32_e32 v153, 1.0, v153
	v_log_f32_e32 v153, v153
	s_nop 0
	v_cndmask_b32_e64 v153, v153, v124, s[34:35]
	v_subrev_u32_e32 v124, 50, v128
	v_cmp_lt_i32_e64 s[34:35], v124, v101
	s_or_b64 s[34:35], vcc, s[34:35]
	v_fma_f32 v75, v75, s98, -v153
	v_cndmask_b32_e64 v154, 0, -v153, s[34:35]
	v_add_f32_e32 v153, v154, v126
	v_mul_f32_e32 v126, 0x3e38aa3b, v76
	v_exp_f32_e32 v155, v126
	v_cmp_lt_f32_e64 s[36:37], s99, v126
	v_add_f32_e32 v155, 1.0, v155
	v_log_f32_e32 v155, v155
	s_nop 0
	v_cndmask_b32_e64 v155, v155, v126, s[36:37]
	v_subrev_u32_e32 v126, 49, v128
	v_cmp_lt_i32_e64 s[36:37], v126, v101
	s_or_b64 s[36:37], vcc, s[36:37]
	v_fma_f32 v76, v76, s98, -v155
	v_cndmask_b32_e64 v156, 0, -v155, s[36:37]
	v_mul_f32_e32 v155, 0x3e38aa3b, v77
	v_exp_f32_e32 v157, v155
	v_cmp_lt_f32_e64 s[38:39], s99, v155
	v_subrev_u32_e32 v128, 48, v128
	v_add_f32_e32 v153, v156, v153
	v_add_f32_e32 v157, 1.0, v157
	v_log_f32_e32 v157, v157
	s_nop 0
	v_cndmask_b32_e64 v155, v157, v155, s[38:39]
	v_cmp_lt_i32_e64 s[38:39], v128, v101
	s_or_b64 s[38:39], vcc, s[38:39]
	v_fma_f32 v77, v77, s98, -v155
	v_cndmask_b32_e64 v157, 0, -v155, s[38:39]
	v_add_f32_e32 v153, v157, v153
	ds_bpermute_b32 v155, v116, v153
	ds_bpermute_b32 v158, v119, v153
	ds_bpermute_b32 v159, v118, v153
	s_waitcnt lgkmcnt(2)
	v_cndmask_b32_e64 v155, v155, 0, s[0:1]
	s_waitcnt lgkmcnt(1)
	v_cndmask_b32_e64 v158, 0, v158, s[2:3]
	v_add_f32_e32 v155, v155, v158
	s_waitcnt lgkmcnt(0)
	v_cndmask_b32_e64 v158, 0, v159, s[4:5]
	v_add_f32_e32 v155, v155, v158
	v_add_f32_e32 v155, v111, v155
	v_add_f32_e32 v77, v77, v155
	v_add_f32_e32 v155, v157, v155
	v_add_f32_e32 v76, v76, v155
	v_exp_f32_e32 v76, v76
	ds_bpermute_b32 v158, v115, v153
	v_exp_f32_e32 v77, v77
	v_cndmask_b32_e64 v157, 0, v76, s[36:37]
	v_add_f32_e32 v76, v156, v155
	v_add_f32_e32 v75, v75, v76
	v_exp_f32_e32 v75, v75
	s_waitcnt lgkmcnt(0)
	v_add_f32_e32 v153, v153, v158
	ds_bpermute_b32 v158, v117, v153
	v_cndmask_b32_e64 v77, 0, v77, s[38:39]
	v_cndmask_b32_e64 v155, 0, v75, s[34:35]
	v_add_f32_e32 v75, v154, v76
	v_add_f32_e32 v74, v74, v75
	v_exp_f32_e32 v74, v74
	v_cvt_pk_bf16_f32 v77, v157, v77
	v_cndmask_b32_e64 v76, 0, v74, s[30:31]
	v_add_f32_e32 v74, v152, v75
	v_add_f32_e32 v75, v81, v74
	v_add_f32_e32 v74, v151, v74
	v_add_f32_e32 v80, v80, v74
	v_add_f32_e32 v74, v150, v74
	v_add_f32_e32 v79, v79, v74
	v_add_f32_e32 v74, v149, v74
	v_add_f32_e32 v78, v78, v74
	v_exp_f32_e32 v78, v78
	v_add_f32_e32 v74, v148, v74
	v_exp_f32_e32 v80, v80
	v_exp_f32_e32 v79, v79
	v_cndmask_b32_e64 v149, 0, v78, s[22:23]
	v_add_f32_e32 v78, v147, v74
	v_exp_f32_e32 v78, v78
	v_add_f32_e32 v74, v146, v74
	v_cndmask_b32_e64 v151, 0, v80, s[26:27]
	v_cndmask_b32_e64 v150, 0, v79, s[24:25]
	v_cndmask_b32_e64 v81, 0, v78, s[20:21]
	v_add_f32_e32 v78, v145, v74
	v_exp_f32_e32 v78, v78
	v_add_f32_e32 v74, v144, v74
	v_exp_f32_e32 v75, v75
	v_cvt_pk_bf16_f32 v76, v76, v155
	v_cndmask_b32_e64 v145, 0, v78, s[18:19]
	v_add_f32_e32 v78, v143, v74
	v_exp_f32_e32 v78, v78
	v_add_f32_e32 v74, v142, v74
	v_cndmask_b32_e64 v75, 0, v75, s[28:29]
	v_cvt_pk_bf16_f32 v81, v145, v81
	v_cndmask_b32_e64 v80, 0, v78, s[16:17]
	v_add_f32_e32 v78, v141, v74
	v_exp_f32_e32 v78, v78
	v_add_f32_e32 v74, v140, v74
	v_cvt_pk_bf16_f32 v75, v151, v75
	v_cndmask_b32_e64 v141, 0, v78, s[14:15]
	v_add_f32_e32 v78, v138, v74
	v_exp_f32_e32 v78, v78
	v_add_f32_e32 v74, v137, v74
	v_cvt_pk_bf16_f32 v80, v141, v80
	v_cndmask_b32_e64 v79, 0, v78, s[12:13]
	v_add_f32_e32 v78, v136, v74
	v_exp_f32_e32 v78, v78
	v_add_f32_e32 v74, v134, v74
	v_cndmask_b32_e64 v136, 0, v78, s[10:11]
	v_add_f32_e32 v78, v133, v74
	v_add_f32_e32 v74, v132, v74
	v_add_f32_e32 v74, v131, v74
	s_waitcnt lgkmcnt(0)
; __device__ __forceinline__ void sb_mfma(int zz, const Params& p, int bh, int qb, char* shm) {
;     ...
;         float L[16], X[16];
;         float T = 0.f;
; #pragma unroll
;         for (int m = 0; m < 4; ++m)
; #pragma unroll
;           for (int j = 0; j < 4; ++j) {
;             const int i = m * 4 + j;
;             float z2 = z[m][n][j] * cs;
;             float e = __builtin_amdgcn_exp2f(z2);
;             float l2 = __builtin_amdgcn_logf(1.0f + e);
;             l2 = (z2 > 60.f) ? z2 : l2;
;             float Lv = -l2;
;             if (diag) Lv = (key0 + i < tq) ? Lv : 0.f;
;             L[i] = Lv;
;             X[i] = z2 - l2;
;             T += Lv;
;           }
;         float t1 = __shfl(T, lane + 16, 64), t2 = __shfl(T, lane + 32, 64), t3 = __shfl(T, lane + 48, 64);
;         float suf = ((fq < 3) ? t1 : 0.f) + ((fq < 2) ? t2 : 0.f) + ((fq < 1) ? t3 : 0.f);
;         float tot = T + __shfl_xor(T, 16, 64);
;         tot += __shfl_xor(tot, 32, 64);
;         float run = R[n] + suf;
;         float A[16];
; #pragma unroll
;         for (int i = 15; i >= 0; --i) {
;           float a = __builtin_amdgcn_exp2f(X[i] + run);
;           if (diag) a = (key0 + i < tq) ? a : 0.f;
;           A[i] = a;
;           run += L[i];
;         }
	v_add_f32_e32 v131, v153, v158
	v_add_f32_e32 v111, v111, v131
	v_mul_f32_e32 v131, 0x3e38aa3b, v70
	v_exp_f32_e32 v132, v131
	v_exp_f32_e32 v74, v74
	v_exp_f32_e32 v78, v78
	v_cvt_pk_bf16_f32 v79, v136, v79
	v_add_f32_e32 v132, 1.0, v132
	v_log_f32_e32 v132, v132
	v_cndmask_b32_e64 v74, 0, v74, s[6:7]
	v_cmp_lt_f32_e64 s[6:7], s99, v131
	v_cndmask_b32_e64 v78, 0, v78, s[8:9]
	v_cvt_pk_bf16_f32 v78, v74, v78
	v_cndmask_b32_e64 v131, v132, v131, s[6:7]
	v_cmp_lt_i32_e64 s[6:7], v121, v114
	v_fma_f32 v70, v70, s98, -v131
	v_sub_f32_e32 v121, 0, v131
	v_mul_f32_e32 v131, 0x3e38aa3b, v71
	v_exp_f32_e32 v132, v131
	v_cmp_lt_f32_e64 s[8:9], s99, v131
	s_or_b64 s[6:7], vcc, s[6:7]
	v_cndmask_b32_e64 v121, 0, v121, s[6:7]
	v_add_f32_e32 v132, 1.0, v132
	v_log_f32_e32 v132, v132
	v_cvt_pk_bf16_f32 v74, v149, v150
	v_cndmask_b32_e64 v131, v132, v131, s[8:9]
	v_cmp_lt_i32_e64 s[8:9], v86, v114
	s_or_b64 s[8:9], vcc, s[8:9]
	v_fma_f32 v71, v71, s98, -v131
	v_cndmask_b32_e64 v86, 0, -v131, s[8:9]
	v_mul_f32_e32 v131, 0x3e38aa3b, v72
	v_exp_f32_e32 v132, v131
	v_cmp_lt_f32_e64 s[10:11], s99, v131
	v_add_f32_e32 v121, v86, v121
	v_add_f32_e32 v132, 1.0, v132
	v_log_f32_e32 v132, v132
	s_nop 0
	v_cndmask_b32_e64 v131, v132, v131, s[10:11]
	v_cmp_lt_i32_e64 s[10:11], v87, v114
	s_or_b64 s[10:11], vcc, s[10:11]
	v_fma_f32 v72, v72, s98, -v131
	v_cndmask_b32_e64 v87, 0, -v131, s[10:11]
	v_mul_f32_e32 v131, 0x3e38aa3b, v73
	v_exp_f32_e32 v132, v131
	v_cmp_lt_f32_e64 s[12:13], s99, v131
	v_add_f32_e32 v121, v87, v121
	v_add_f32_e32 v132, 1.0, v132
	v_log_f32_e32 v132, v132
	s_nop 0
	v_cndmask_b32_e64 v131, v132, v131, s[12:13]
	v_cmp_lt_i32_e64 s[12:13], v88, v114
	s_or_b64 s[12:13], vcc, s[12:13]
	v_fma_f32 v73, v73, s98, -v131
	v_cndmask_b32_e64 v88, 0, -v131, s[12:13]
	v_mul_f32_e32 v131, 0x3e38aa3b, v66
	v_exp_f32_e32 v132, v131
	v_cmp_lt_f32_e64 s[14:15], s99, v131
	v_add_f32_e32 v121, v88, v121
	v_add_f32_e32 v132, 1.0, v132
	v_log_f32_e32 v132, v132
	s_nop 0
	v_cndmask_b32_e64 v131, v132, v131, s[14:15]
	v_cmp_lt_i32_e64 s[14:15], v89, v114
	s_or_b64 s[14:15], vcc, s[14:15]
	v_fma_f32 v66, v66, s98, -v131
	v_cndmask_b32_e64 v89, 0, -v131, s[14:15]
	v_mul_f32_e32 v131, 0x3e38aa3b, v67
	v_exp_f32_e32 v132, v131
	v_cmp_lt_f32_e64 s[16:17], s99, v131
	v_add_f32_e32 v121, v89, v121
	v_add_f32_e32 v132, 1.0, v132
	v_log_f32_e32 v132, v132
	s_nop 0
	v_cndmask_b32_e64 v131, v132, v131, s[16:17]
	v_cmp_lt_i32_e64 s[16:17], v82, v114
	s_or_b64 s[16:17], vcc, s[16:17]
	v_fma_f32 v67, v67, s98, -v131
	v_cndmask_b32_e64 v82, 0, -v131, s[16:17]
	v_mul_f32_e32 v131, 0x3e38aa3b, v68
	v_exp_f32_e32 v132, v131
	v_cmp_lt_f32_e64 s[18:19], s99, v131
	v_add_f32_e32 v121, v82, v121
	v_add_f32_e32 v132, 1.0, v132
	v_log_f32_e32 v132, v132
	s_nop 0
	v_cndmask_b32_e64 v131, v132, v131, s[18:19]
	v_cmp_lt_i32_e64 s[18:19], v83, v114
	s_or_b64 s[18:19], vcc, s[18:19]
	v_fma_f32 v68, v68, s98, -v131
	v_cndmask_b32_e64 v83, 0, -v131, s[18:19]
	v_mul_f32_e32 v131, 0x3e38aa3b, v69
	v_exp_f32_e32 v132, v131
	v_cmp_lt_f32_e64 s[20:21], s99, v131
	v_add_f32_e32 v121, v83, v121
	v_add_f32_e32 v132, 1.0, v132
	v_log_f32_e32 v132, v132
	s_nop 0
	v_cndmask_b32_e64 v131, v132, v131, s[20:21]
	v_cmp_lt_i32_e64 s[20:21], v84, v114
	s_or_b64 s[20:21], vcc, s[20:21]
	v_fma_f32 v69, v69, s98, -v131
	v_cndmask_b32_e64 v84, 0, -v131, s[20:21]
	v_mul_f32_e32 v131, 0x3e38aa3b, v62
	v_exp_f32_e32 v132, v131
	v_cmp_lt_f32_e64 s[22:23], s99, v131
	v_add_f32_e32 v121, v84, v121
	v_add_f32_e32 v132, 1.0, v132
	v_log_f32_e32 v132, v132
	s_nop 0
	v_cndmask_b32_e64 v131, v132, v131, s[22:23]
	v_cmp_lt_i32_e64 s[22:23], v120, v114
	s_or_b64 s[22:23], vcc, s[22:23]
	v_fma_f32 v62, v62, s98, -v131
	v_cndmask_b32_e64 v120, 0, -v131, s[22:23]
	v_mul_f32_e32 v131, 0x3e38aa3b, v63
	v_exp_f32_e32 v132, v131
	v_cmp_lt_f32_e64 s[24:25], s99, v131
	v_add_f32_e32 v121, v120, v121
	v_add_f32_e32 v132, 1.0, v132
	v_log_f32_e32 v132, v132
	s_nop 0
	v_cndmask_b32_e64 v131, v132, v131, s[24:25]
	v_cmp_lt_i32_e64 s[24:25], v85, v114
	s_or_b64 s[24:25], vcc, s[24:25]
	v_fma_f32 v63, v63, s98, -v131
	v_cndmask_b32_e64 v85, 0, -v131, s[24:25]
	v_mul_f32_e32 v131, 0x3e38aa3b, v64
	v_exp_f32_e32 v132, v131
	v_cmp_lt_f32_e64 s[26:27], s99, v131
	v_add_f32_e32 v121, v85, v121
	v_add_f32_e32 v132, 1.0, v132
	v_log_f32_e32 v132, v132
	s_nop 0
	v_cndmask_b32_e64 v131, v132, v131, s[26:27]
	v_cmp_lt_i32_e64 s[26:27], v122, v114
	s_or_b64 s[26:27], vcc, s[26:27]
	v_fma_f32 v64, v64, s98, -v131
	v_cndmask_b32_e64 v122, 0, -v131, s[26:27]
	v_mul_f32_e32 v131, 0x3e38aa3b, v65
	v_exp_f32_e32 v132, v131
	v_cmp_lt_f32_e64 s[28:29], s99, v131
	v_add_f32_e32 v121, v122, v121
	v_add_f32_e32 v132, 1.0, v132
	v_log_f32_e32 v132, v132
	s_nop 0
	v_cndmask_b32_e64 v131, v132, v131, s[28:29]
	v_cmp_lt_i32_e64 s[28:29], v123, v114
	s_or_b64 s[28:29], vcc, s[28:29]
	v_fma_f32 v65, v65, s98, -v131
	v_cndmask_b32_e64 v123, 0, -v131, s[28:29]
	v_mul_f32_e32 v131, 0x3e38aa3b, v58
	v_exp_f32_e32 v132, v131
	v_cmp_lt_f32_e64 s[30:31], s99, v131
	v_add_f32_e32 v121, v123, v121
	v_add_f32_e32 v132, 1.0, v132
	v_log_f32_e32 v132, v132
	s_nop 0
	v_cndmask_b32_e64 v131, v132, v131, s[30:31]
	v_cmp_lt_i32_e64 s[30:31], v127, v114
	s_or_b64 s[30:31], vcc, s[30:31]
	v_fma_f32 v58, v58, s98, -v131
	v_cndmask_b32_e64 v127, 0, -v131, s[30:31]
	v_mul_f32_e32 v131, 0x3e38aa3b, v59
	v_exp_f32_e32 v132, v131
	v_cmp_lt_f32_e64 s[34:35], s99, v131
	v_add_f32_e32 v121, v127, v121
	v_add_f32_e32 v132, 1.0, v132
	v_log_f32_e32 v132, v132
	s_nop 0
	v_cndmask_b32_e64 v131, v132, v131, s[34:35]
	v_cmp_lt_i32_e64 s[34:35], v124, v114
	s_or_b64 s[34:35], vcc, s[34:35]
	v_fma_f32 v59, v59, s98, -v131
	v_cndmask_b32_e64 v124, 0, -v131, s[34:35]
	v_mul_f32_e32 v131, 0x3e38aa3b, v60
	v_exp_f32_e32 v132, v131
	v_cmp_lt_f32_e64 s[36:37], s99, v131
	v_add_f32_e32 v121, v124, v121
	v_add_f32_e32 v132, 1.0, v132
	v_log_f32_e32 v132, v132
	s_nop 0
	v_cndmask_b32_e64 v131, v132, v131, s[36:37]
	v_cmp_lt_i32_e64 s[36:37], v126, v114
	s_or_b64 s[36:37], vcc, s[36:37]
	v_fma_f32 v60, v60, s98, -v131
	v_cndmask_b32_e64 v126, 0, -v131, s[36:37]
	v_mul_f32_e32 v131, 0x3e38aa3b, v61
	v_exp_f32_e32 v132, v131
	v_cmp_lt_f32_e64 s[38:39], s99, v131
	v_add_f32_e32 v121, v126, v121
	v_add_f32_e32 v132, 1.0, v132
	v_log_f32_e32 v132, v132
	s_nop 0
	v_cndmask_b32_e64 v131, v132, v131, s[38:39]
	v_cmp_lt_i32_e64 s[38:39], v128, v114
	s_or_b64 vcc, vcc, s[38:39]
	v_cndmask_b32_e64 v128, 0, -v131, vcc
	v_add_f32_e32 v121, v128, v121
	ds_bpermute_b32 v116, v116, v121
	ds_bpermute_b32 v119, v119, v121
	ds_bpermute_b32 v118, v118, v121
	v_fma_f32 v61, v61, s98, -v131
	ds_bpermute_b32 v115, v115, v121
	s_waitcnt lgkmcnt(3)
; __device__ __forceinline__ void sb_mfma(int zz, const Params& p, int bh, int qb, char* shm) {
;     ...
;         float t1 = __shfl(T, lane + 16, 64), t2 = __shfl(T, lane + 32, 64), t3 = __shfl(T, lane + 48, 64);
;         float suf = ((fq < 3) ? t1 : 0.f) + ((fq < 2) ? t2 : 0.f) + ((fq < 1) ? t3 : 0.f);
;         float tot = T + __shfl_xor(T, 16, 64);
;         tot += __shfl_xor(tot, 32, 64);
;         float run = R[n] + suf;
;         float A[16];
; #pragma unroll
;         for (int i = 15; i >= 0; --i) {
;           float a = __builtin_amdgcn_exp2f(X[i] + run);
;           if (diag) a = (key0 + i < tq) ? a : 0.f;
;           A[i] = a;
;           run += L[i];
;         }
;         R[n] += tot;
; #pragma unroll
;         for (int kk = 0; kk < 2; ++kk) {
;           union { bf16x8 v; unsigned u[4]; } cv;
; #pragma unroll
;           for (int c = 0; c < 4; ++c) cv.u[c] = pack2(A[kk * 8 + 2 * c], A[kk * 8 + 2 * c + 1]);
;           pa[n][kk] = cv.v;
;         }
;       }
; #pragma unroll
;       for (int kk = 0; kk < 2; ++kk) {
;         bf16x8 vf[4];
; #pragma unroll
;         for (int md = 0; md < 4; ++md) vf[md] = *(const bf16x8*)(vsb + (md * 16 + fr) * 72 + fq * 16 + kk * 8);
; #pragma unroll
;         for (int md = 0; md < 4; ++md)
; #pragma unroll
;           for (int n = 0; n < 2; ++n) o[md][n] = __builtin_amdgcn_mfma_f32_16x16x32_bf16(vf[md], pa[n][kk], o[md][n], 0, 0, 0);
;       }
	v_cndmask_b32_e64 v116, v116, 0, s[0:1]
	s_waitcnt lgkmcnt(2)
	v_cndmask_b32_e64 v119, 0, v119, s[2:3]
	v_add_f32_e32 v116, v116, v119
	s_waitcnt lgkmcnt(1)
	v_cndmask_b32_e64 v118, 0, v118, s[4:5]
	v_add_f32_e32 v116, v116, v118
	v_add_f32_e32 v116, v112, v116
	v_add_f32_e32 v61, v61, v116
	v_add_f32_e32 v116, v128, v116
	v_add_f32_e32 v60, v60, v116
	v_exp_f32_e32 v60, v60
	s_waitcnt lgkmcnt(0)
	v_add_f32_e32 v115, v121, v115
	ds_bpermute_b32 v117, v117, v115
	v_exp_f32_e32 v61, v61
	v_cndmask_b32_e64 v118, 0, v60, s[36:37]
	v_add_f32_e32 v60, v126, v116
	v_add_f32_e32 v59, v59, v60
	v_exp_f32_e32 v59, v59
	v_cndmask_b32_e32 v61, 0, v61, vcc
	v_cvt_pk_bf16_f32 v61, v118, v61
	v_cndmask_b32_e64 v116, 0, v59, s[34:35]
	v_add_f32_e32 v59, v124, v60
	v_add_f32_e32 v58, v58, v59
	v_exp_f32_e32 v58, v58
	s_nop 0
	v_cndmask_b32_e64 v60, 0, v58, s[30:31]
	v_add_f32_e32 v58, v127, v59
	v_add_f32_e32 v59, v65, v58
	v_add_f32_e32 v58, v123, v58
	v_add_f32_e32 v64, v64, v58
	v_add_f32_e32 v58, v122, v58
	v_add_f32_e32 v63, v63, v58
	v_add_f32_e32 v58, v85, v58
	v_add_f32_e32 v62, v62, v58
	v_exp_f32_e32 v62, v62
	v_add_f32_e32 v58, v120, v58
	v_exp_f32_e32 v64, v64
	v_exp_f32_e32 v63, v63
	v_cndmask_b32_e64 v85, 0, v62, s[22:23]
	v_add_f32_e32 v62, v69, v58
	v_exp_f32_e32 v62, v62
	v_add_f32_e32 v58, v84, v58
	v_cndmask_b32_e64 v119, 0, v64, s[26:27]
	v_cndmask_b32_e64 v121, 0, v63, s[24:25]
	v_cndmask_b32_e64 v65, 0, v62, s[20:21]
	v_add_f32_e32 v62, v68, v58
	v_exp_f32_e32 v62, v62
	v_add_f32_e32 v58, v83, v58
	v_exp_f32_e32 v59, v59
	s_waitcnt lgkmcnt(0)
	v_add_f32_e32 v69, v115, v117
	v_cndmask_b32_e64 v68, 0, v62, s[18:19]
	v_add_f32_e32 v62, v67, v58
	v_exp_f32_e32 v62, v62
	v_add_f32_e32 v58, v82, v58
	v_cndmask_b32_e64 v59, 0, v59, s[28:29]
	v_add_f32_e32 v112, v112, v69
	v_cndmask_b32_e64 v64, 0, v62, s[16:17]
	v_add_f32_e32 v62, v66, v58
	v_exp_f32_e32 v62, v62
	v_add_f32_e32 v58, v89, v58
	v_cvt_pk_bf16_f32 v65, v68, v65
	v_cvt_pk_bf16_f32 v59, v119, v59
	v_cndmask_b32_e64 v66, 0, v62, s[14:15]
	v_add_f32_e32 v62, v73, v58
	v_exp_f32_e32 v62, v62
	v_add_f32_e32 v58, v88, v58
	v_cvt_pk_bf16_f32 v64, v66, v64
	v_or_b32_e32 v66, s85, v109
	v_cndmask_b32_e64 v63, 0, v62, s[12:13]
	v_add_f32_e32 v62, v72, v58
	v_exp_f32_e32 v62, v62
	v_add_f32_e32 v58, v87, v58
	v_add_u32_e32 v115, v66, v125
	v_cvt_pk_bf16_f32 v60, v60, v116
	v_cndmask_b32_e64 v67, 0, v62, s[10:11]
	v_add_f32_e32 v62, v71, v58
	v_add_f32_e32 v58, v86, v58
	v_add_f32_e32 v58, v70, v58
	v_exp_f32_e32 v62, v62
	v_exp_f32_e32 v58, v58
	v_cvt_pk_bf16_f32 v63, v67, v63
	v_cndmask_b32_e64 v62, 0, v62, s[8:9]
	v_cndmask_b32_e64 v58, 0, v58, s[6:7]
	v_cvt_pk_bf16_f32 v62, v58, v62
	v_cvt_pk_bf16_f32 v58, v85, v121
	ds_read_b128 v[66:69], v115 offset:20736
	ds_read_b128 v[70:73], v115 offset:23040
	ds_read_b128 v[82:85], v115 offset:25344
	ds_read_b128 v[86:89], v115 offset:18432
	ds_read_b128 v[116:119], v115 offset:18448
	s_waitcnt lgkmcnt(1)
	v_mfma_f32_16x16x32_bf16 v[26:29], v[86:89], v[62:65], v[26:29]
	v_mfma_f32_16x16x32_bf16 v[38:41], v[66:69], v[78:81], v[38:41]
	v_mfma_f32_16x16x32_bf16 v[34:37], v[66:69], v[62:65], v[34:37]
	v_mfma_f32_16x16x32_bf16 v[46:49], v[70:73], v[78:81], v[46:49]
	v_mfma_f32_16x16x32_bf16 v[42:45], v[70:73], v[62:65], v[42:45]
	v_mfma_f32_16x16x32_bf16 v[54:57], v[82:85], v[62:65], v[54:57]
	ds_read_b128 v[62:65], v115 offset:20752
	ds_read_b128 v[66:69], v115 offset:23056
	ds_read_b128 v[70:73], v115 offset:25360
	v_mfma_f32_16x16x32_bf16 v[30:33], v[86:89], v[78:81], v[30:33]
	v_mfma_f32_16x16x32_bf16 v[50:53], v[82:85], v[78:81], v[50:53]
	s_waitcnt lgkmcnt(3)
	v_mfma_f32_16x16x32_bf16 v[30:33], v[116:119], v[74:77], v[30:33]
	v_mfma_f32_16x16x32_bf16 v[26:29], v[116:119], v[58:61], v[26:29]
	s_waitcnt lgkmcnt(2)
	v_mfma_f32_16x16x32_bf16 v[38:41], v[62:65], v[74:77], v[38:41]
	v_mfma_f32_16x16x32_bf16 v[34:37], v[62:65], v[58:61], v[34:37]
	s_waitcnt lgkmcnt(1)
	v_mfma_f32_16x16x32_bf16 v[46:49], v[66:69], v[74:77], v[46:49]
	v_mfma_f32_16x16x32_bf16 v[42:45], v[66:69], v[58:61], v[42:45]
	s_waitcnt lgkmcnt(0)
	v_mfma_f32_16x16x32_bf16 v[50:53], v[70:73], v[74:77], v[50:53]
	v_mfma_f32_16x16x32_bf16 v[54:57], v[70:73], v[58:61], v[54:57]

; __device__ __forceinline__ void sb_mfma(int zz, const Params& p, int bh, int qb, char* shm) {
;     ...
; #pragma unroll
;       for (int m = 0; m < 4; ++m)
; #pragma unroll
;         for (int n = 0; n < 2; ++n) z[m][n] = f32x4{0.f, 0.f, 0.f, 0.f};
; #pragma unroll
;       for (int ds = 0; ds < 2; ++ds) {
;         bf16x8 kf[4];
; #pragma unroll
;         for (int m = 0; m < 4; ++m) kf[m] = *(const bf16x8*)(ksb + (m * 16 + fr) * 72 + ds * 32 + fq * 8);
; #pragma unroll
;         for (int m = 0; m < 4; ++m)
; #pragma unroll
;           for (int n = 0; n < 2; ++n) z[m][n] = __builtin_amdgcn_mfma_f32_16x16x32_bf16(kf[m], qf[n][ds], z[m][n], 0, 0, 0);
;       }
;       const bool diag = (kbase + 63 >= tq0);
;       bf16x8 pa[2][2];
; #pragma unroll
;       for (int n = 0; n < 2; ++n) {
;         const int tq = tq0 + n * 16 + fr;
;         const int key0 = kbase + fq * 16;
;         float L[16], X[16];
;         float T = 0.f;
; #pragma unroll
;         for (int m = 0; m < 4; ++m)
; #pragma unroll
;           for (int j = 0; j < 4; ++j) {
;             const int i = m * 4 + j;
;             float z2 = z[m][n][j] * cs;
;             float e = __builtin_amdgcn_exp2f(z2);
;             float l2 = __builtin_amdgcn_logf(1.0f + e);
;             l2 = (z2 > 60.f) ? z2 : l2;
;             float Lv = -l2;
;             if (diag) Lv = (key0 + i < tq) ? Lv : 0.f;
;             L[i] = Lv;
;             X[i] = z2 - l2;
;             T += Lv;
;           }
.Lsb_fast:
	s_xor_b32 s85, s84, 1
	s_mulk_i32 s85, 0x2400
	v_or_b32_e32 v115, s85, v98
	v_add_u32_e32 v115, v115, v125
	ds_read_b128 v[58:61], v115 offset:6912
	ds_read_b128 v[62:65], v115 offset:4608
	ds_read_b128 v[66:69], v115 offset:2304
	ds_read_b128 v[70:73], v115
	ds_read_b128 v[116:119], v115 offset:6976
	ds_read_b128 v[120:123], v115 offset:4672
	v_lshlrev_b32_e32 v131, 2, v107
	v_lshlrev_b32_e32 v133, 2, v108
	v_lshlrev_b32_e32 v134, 2, v99
	v_xor_b32_e32 v132, 0x80, v134
	v_xor_b32_e32 v134, 64, v134
	v_or_b32_e32 v124, s85, v109
	v_add_u32_e32 v124, v124, v125
	s_waitcnt lgkmcnt(5)
	v_mfma_f32_16x16x32_bf16 v[140:143], v[58:61], v[2:5], 0
	v_mfma_f32_16x16x32_bf16 v[74:77], v[58:61], v[10:13], 0
	ds_read_b128 v[58:61], v115 offset:2368
	s_waitcnt lgkmcnt(5)
	v_mfma_f32_16x16x32_bf16 v[144:147], v[62:65], v[2:5], 0
	v_mfma_f32_16x16x32_bf16 v[78:81], v[62:65], v[10:13], 0
	ds_read_b128 v[62:65], v115 offset:64
	s_waitcnt lgkmcnt(5)
	v_mfma_f32_16x16x32_bf16 v[148:151], v[66:69], v[2:5], 0
	v_mfma_f32_16x16x32_bf16 v[82:85], v[66:69], v[10:13], 0
	s_waitcnt lgkmcnt(4)
	v_mfma_f32_16x16x32_bf16 v[152:155], v[70:73], v[2:5], 0
	v_mfma_f32_16x16x32_bf16 v[86:89], v[70:73], v[10:13], 0
	s_waitcnt lgkmcnt(3)
	v_mfma_f32_16x16x32_bf16 v[140:143], v[116:119], v[6:9], v[140:143]
	v_mfma_f32_16x16x32_bf16 v[74:77], v[116:119], v[14:17], v[74:77]
	s_waitcnt lgkmcnt(2)
	v_mfma_f32_16x16x32_bf16 v[144:147], v[120:123], v[6:9], v[144:147]
	v_mfma_f32_16x16x32_bf16 v[78:81], v[120:123], v[14:17], v[78:81]
	s_waitcnt lgkmcnt(1)
	v_mfma_f32_16x16x32_bf16 v[148:151], v[58:61], v[6:9], v[148:151]
	v_mfma_f32_16x16x32_bf16 v[82:85], v[58:61], v[14:17], v[82:85]
	s_waitcnt lgkmcnt(0)
	v_mfma_f32_16x16x32_bf16 v[152:155], v[62:65], v[6:9], v[152:155]
	v_mfma_f32_16x16x32_bf16 v[86:89], v[62:65], v[14:17], v[86:89]
	ds_read_b128 v[58:61], v124 offset:18432
	ds_read_b128 v[62:65], v124 offset:20736
	ds_read_b128 v[66:69], v124 offset:23040
	ds_read_b128 v[70:73], v124 offset:25344
	v_mov_b32_e32 v136, 1.0
	v_mul_f32_e32 v143, s98, v143
	v_mul_f32_e32 v142, s98, v142
	v_mul_f32_e32 v141, s98, v141
	v_mul_f32_e32 v140, s98, v140
	v_min_f32_e32 v143, s99, v143
	v_min_f32_e32 v142, s99, v142
	v_min_f32_e32 v141, s99, v141
	v_min_f32_e32 v140, s99, v140
	v_exp_f32_e32 v143, v143
	v_exp_f32_e32 v142, v142
	v_exp_f32_e32 v141, v141
	v_exp_f32_e32 v140, v140
	v_add_f32_e32 v115, 1.0, v143
	v_add_f32_e32 v127, 1.0, v142
	v_add_f32_e32 v128, 1.0, v141
	v_add_f32_e32 v137, 1.0, v140
	v_rcp_f32_e32 v115, v115
	v_rcp_f32_e32 v127, v127
	v_rcp_f32_e32 v128, v128
	v_rcp_f32_e32 v137, v137
	v_mul_f32_e32 v136, v136, v115
	v_mul_f32_e32 v143, v143, v136
	v_mul_f32_e32 v136, v136, v127
	v_mul_f32_e32 v142, v142, v136
	v_mul_f32_e32 v136, v136, v128
	v_mul_f32_e32 v141, v141, v136
	v_mul_f32_e32 v136, v136, v137
	v_mul_f32_e32 v140, v140, v136
	v_mul_f32_e32 v147, s98, v147
	v_mul_f32_e32 v146, s98, v146
	v_mul_f32_e32 v145, s98, v145
	v_mul_f32_e32 v144, s98, v144
	v_min_f32_e32 v147, s99, v147
	v_min_f32_e32 v146, s99, v146
	v_min_f32_e32 v145, s99, v145
	v_min_f32_e32 v144, s99, v144
	v_exp_f32_e32 v147, v147
	v_exp_f32_e32 v146, v146
	v_exp_f32_e32 v145, v145
	v_exp_f32_e32 v144, v144
	v_add_f32_e32 v115, 1.0, v147
	v_add_f32_e32 v127, 1.0, v146
	v_add_f32_e32 v128, 1.0, v145
	v_add_f32_e32 v137, 1.0, v144
	v_rcp_f32_e32 v115, v115
	v_rcp_f32_e32 v127, v127
	v_rcp_f32_e32 v128, v128
	v_rcp_f32_e32 v137, v137
	v_mul_f32_e32 v136, v136, v115
	v_mul_f32_e32 v147, v147, v136
	v_mul_f32_e32 v136, v136, v127
	v_mul_f32_e32 v146, v146, v136
	v_mul_f32_e32 v136, v136, v128
	v_mul_f32_e32 v145, v145, v136
	v_mul_f32_e32 v136, v136, v137
	v_mul_f32_e32 v144, v144, v136
	v_mul_f32_e32 v151, s98, v151
	v_mul_f32_e32 v150, s98, v150
	v_mul_f32_e32 v149, s98, v149
	v_mul_f32_e32 v148, s98, v148
	v_min_f32_e32 v151, s99, v151
	v_min_f32_e32 v150, s99, v150
	v_min_f32_e32 v149, s99, v149
	v_min_f32_e32 v148, s99, v148
	v_exp_f32_e32 v151, v151
	v_exp_f32_e32 v150, v150
	v_exp_f32_e32 v149, v149
	v_exp_f32_e32 v148, v148
	v_add_f32_e32 v115, 1.0, v151
	v_add_f32_e32 v127, 1.0, v150
	v_add_f32_e32 v128, 1.0, v149
	v_add_f32_e32 v137, 1.0, v148
	v_rcp_f32_e32 v115, v115
	v_rcp_f32_e32 v127, v127
	v_rcp_f32_e32 v128, v128
	v_rcp_f32_e32 v137, v137
	v_mul_f32_e32 v136, v136, v115
	v_mul_f32_e32 v151, v151, v136
	v_mul_f32_e32 v136, v136, v127
	v_mul_f32_e32 v150, v150, v136
	v_mul_f32_e32 v136, v136, v128
	v_mul_f32_e32 v149, v149, v136
	v_mul_f32_e32 v136, v136, v137
	v_mul_f32_e32 v148, v148, v136
	v_mul_f32_e32 v155, s98, v155
	v_mul_f32_e32 v154, s98, v154
	v_mul_f32_e32 v153, s98, v153
	v_mul_f32_e32 v152, s98, v152
	v_min_f32_e32 v155, s99, v155
	v_min_f32_e32 v154, s99, v154
	v_min_f32_e32 v153, s99, v153
	v_min_f32_e32 v152, s99, v152
	v_exp_f32_e32 v155, v155
	v_exp_f32_e32 v154, v154
	v_exp_f32_e32 v153, v153
	v_exp_f32_e32 v152, v152
	v_add_f32_e32 v115, 1.0, v155
	v_add_f32_e32 v127, 1.0, v154
	v_add_f32_e32 v128, 1.0, v153
	v_add_f32_e32 v137, 1.0, v152
	v_rcp_f32_e32 v115, v115
	v_rcp_f32_e32 v127, v127
	v_rcp_f32_e32 v128, v128
	v_rcp_f32_e32 v137, v137
	v_mul_f32_e32 v136, v136, v115
	v_mul_f32_e32 v155, v155, v136
	v_mul_f32_e32 v136, v136, v127
	v_mul_f32_e32 v154, v154, v136
	v_mul_f32_e32 v136, v136, v128
	v_mul_f32_e32 v153, v153, v136
	v_mul_f32_e32 v136, v136, v137
	v_mul_f32_e32 v152, v152, v136
	ds_bpermute_b32 v116, v131, v136
	ds_bpermute_b32 v117, v132, v136
	ds_bpermute_b32 v118, v133, v136
	ds_bpermute_b32 v119, v134, v136
	v_mov_b32_e32 v138, 1.0
	v_mul_f32_e32 v77, s98, v77
	v_mul_f32_e32 v76, s98, v76
	v_mul_f32_e32 v75, s98, v75
	v_mul_f32_e32 v74, s98, v74
; __device__ __forceinline__ void sb_mfma(int zz, const Params& p, int bh, int qb, char* shm) {
;     ...
;         float t1 = __shfl(T, lane + 16, 64), t2 = __shfl(T, lane + 32, 64), t3 = __shfl(T, lane + 48, 64);
;         float suf = ((fq < 3) ? t1 : 0.f) + ((fq < 2) ? t2 : 0.f) + ((fq < 1) ? t3 : 0.f);
;         float tot = T + __shfl_xor(T, 16, 64);
;         tot += __shfl_xor(tot, 32, 64);
;         float run = R[n] + suf;
;         float A[16];
; #pragma unroll
;         for (int i = 15; i >= 0; --i) {
;           float a = __builtin_amdgcn_exp2f(X[i] + run);
;           if (diag) a = (key0 + i < tq) ? a : 0.f;
;           A[i] = a;
;           run += L[i];
;         }
;         R[n] += tot;
; #pragma unroll
;         for (int kk = 0; kk < 2; ++kk) {
;           union { bf16x8 v; unsigned u[4]; } cv;
; #pragma unroll
;           for (int c = 0; c < 4; ++c) cv.u[c] = pack2(A[kk * 8 + 2 * c], A[kk * 8 + 2 * c + 1]);
;           pa[n][kk] = cv.v;
;         }
;       }
; #pragma unroll
;       for (int kk = 0; kk < 2; ++kk) {
;         bf16x8 vf[4];
; #pragma unroll
;         for (int md = 0; md < 4; ++md) vf[md] = *(const bf16x8*)(vsb + (md * 16 + fr) * 72 + fq * 16 + kk * 8);
; #pragma unroll
;         for (int md = 0; md < 4; ++md)
; #pragma unroll
;           for (int n = 0; n < 2; ++n) o[md][n] = __builtin_amdgcn_mfma_f32_16x16x32_bf16(vf[md], pa[n][kk], o[md][n], 0, 0, 0);
;       }
	v_min_f32_e32 v77, s99, v77
	v_min_f32_e32 v76, s99, v76
	v_min_f32_e32 v75, s99, v75
	v_min_f32_e32 v74, s99, v74
	v_exp_f32_e32 v77, v77
	v_exp_f32_e32 v76, v76
	v_exp_f32_e32 v75, v75
	v_exp_f32_e32 v74, v74
	v_add_f32_e32 v115, 1.0, v77
	v_add_f32_e32 v127, 1.0, v76
	v_add_f32_e32 v128, 1.0, v75
	v_add_f32_e32 v137, 1.0, v74
	v_rcp_f32_e32 v115, v115
	v_rcp_f32_e32 v127, v127
	v_rcp_f32_e32 v128, v128
	v_rcp_f32_e32 v137, v137
	v_mul_f32_e32 v138, v138, v115
	v_mul_f32_e32 v77, v77, v138
	v_mul_f32_e32 v138, v138, v127
	v_mul_f32_e32 v76, v76, v138
	v_mul_f32_e32 v138, v138, v128
	v_mul_f32_e32 v75, v75, v138
	v_mul_f32_e32 v138, v138, v137
	v_mul_f32_e32 v74, v74, v138
	v_mul_f32_e32 v81, s98, v81
	v_mul_f32_e32 v80, s98, v80
	v_mul_f32_e32 v79, s98, v79
	v_mul_f32_e32 v78, s98, v78
	v_min_f32_e32 v81, s99, v81
	v_min_f32_e32 v80, s99, v80
	v_min_f32_e32 v79, s99, v79
	v_min_f32_e32 v78, s99, v78
	v_exp_f32_e32 v81, v81
	v_exp_f32_e32 v80, v80
	v_exp_f32_e32 v79, v79
	v_exp_f32_e32 v78, v78
	v_add_f32_e32 v115, 1.0, v81
	v_add_f32_e32 v127, 1.0, v80
	v_add_f32_e32 v128, 1.0, v79
	v_add_f32_e32 v137, 1.0, v78
	v_rcp_f32_e32 v115, v115
	v_rcp_f32_e32 v127, v127
	v_rcp_f32_e32 v128, v128
	v_rcp_f32_e32 v137, v137
	v_mul_f32_e32 v138, v138, v115
	v_mul_f32_e32 v81, v81, v138
	v_mul_f32_e32 v138, v138, v127
	v_mul_f32_e32 v80, v80, v138
	v_mul_f32_e32 v138, v138, v128
	v_mul_f32_e32 v79, v79, v138
	v_mul_f32_e32 v138, v138, v137
	v_mul_f32_e32 v78, v78, v138
	v_mul_f32_e32 v85, s98, v85
	v_mul_f32_e32 v84, s98, v84
	v_mul_f32_e32 v83, s98, v83
	v_mul_f32_e32 v82, s98, v82
	v_min_f32_e32 v85, s99, v85
	v_min_f32_e32 v84, s99, v84
	v_min_f32_e32 v83, s99, v83
	v_min_f32_e32 v82, s99, v82
	v_exp_f32_e32 v85, v85
	v_exp_f32_e32 v84, v84
	v_exp_f32_e32 v83, v83
	v_exp_f32_e32 v82, v82
	v_add_f32_e32 v115, 1.0, v85
	v_add_f32_e32 v127, 1.0, v84
	v_add_f32_e32 v128, 1.0, v83
	v_add_f32_e32 v137, 1.0, v82
	v_rcp_f32_e32 v115, v115
	v_rcp_f32_e32 v127, v127
	v_rcp_f32_e32 v128, v128
	v_rcp_f32_e32 v137, v137
	v_mul_f32_e32 v138, v138, v115
	v_mul_f32_e32 v85, v85, v138
	v_mul_f32_e32 v138, v138, v127
	v_mul_f32_e32 v84, v84, v138
	v_mul_f32_e32 v138, v138, v128
	v_mul_f32_e32 v83, v83, v138
	v_mul_f32_e32 v138, v138, v137
	v_mul_f32_e32 v82, v82, v138
	v_mul_f32_e32 v89, s98, v89
	v_mul_f32_e32 v88, s98, v88
	v_mul_f32_e32 v87, s98, v87
	v_mul_f32_e32 v86, s98, v86
	v_min_f32_e32 v89, s99, v89
	v_min_f32_e32 v88, s99, v88
	v_min_f32_e32 v87, s99, v87
	v_min_f32_e32 v86, s99, v86
	v_exp_f32_e32 v89, v89
	v_exp_f32_e32 v88, v88
	v_exp_f32_e32 v87, v87
	v_exp_f32_e32 v86, v86
	v_add_f32_e32 v115, 1.0, v89
	v_add_f32_e32 v127, 1.0, v88
	v_add_f32_e32 v128, 1.0, v87
	v_add_f32_e32 v137, 1.0, v86
	v_rcp_f32_e32 v115, v115
	v_rcp_f32_e32 v127, v127
	v_rcp_f32_e32 v128, v128
	v_rcp_f32_e32 v137, v137
	v_mul_f32_e32 v138, v138, v115
	v_mul_f32_e32 v89, v89, v138
	v_mul_f32_e32 v138, v138, v127
	v_mul_f32_e32 v88, v88, v138
	v_mul_f32_e32 v138, v138, v128
	v_mul_f32_e32 v87, v87, v138
	v_mul_f32_e32 v138, v138, v137
	v_mul_f32_e32 v86, v86, v138
	ds_bpermute_b32 v156, v131, v138
	ds_bpermute_b32 v157, v132, v138
	ds_bpermute_b32 v158, v133, v138
	ds_bpermute_b32 v159, v134, v138
	v_exp_f32_e32 v122, v111
	v_exp_f32_e32 v123, v112
	s_waitcnt lgkmcnt(4)
	v_cndmask_b32_e64 v116, v116, 1.0, s[0:1]
	v_cndmask_b32_e64 v117, 1.0, v117, s[2:3]
	v_cndmask_b32_e64 v118, 1.0, v118, s[4:5]
	v_mul_f32_e32 v119, v136, v119
	ds_bpermute_b32 v120, v132, v119
	v_mul_f32_e32 v116, v116, v117
	v_mul_f32_e32 v116, v116, v118
	v_mul_f32_e32 v122, v122, v116
	v_mul_f32_e32 v140, v140, v122
	v_mul_f32_e32 v141, v141, v122
	v_mul_f32_e32 v142, v142, v122
	v_mul_f32_e32 v143, v143, v122
	v_mul_f32_e32 v144, v144, v122
	v_mul_f32_e32 v145, v145, v122
	v_mul_f32_e32 v146, v146, v122
	v_mul_f32_e32 v147, v147, v122
	v_mul_f32_e32 v148, v148, v122
	v_mul_f32_e32 v149, v149, v122
	v_mul_f32_e32 v150, v150, v122
	v_mul_f32_e32 v151, v151, v122
	v_mul_f32_e32 v152, v152, v122
	v_mul_f32_e32 v153, v153, v122
	v_mul_f32_e32 v154, v154, v122
	v_mul_f32_e32 v155, v155, v122
	v_cvt_pk_bf16_f32 v152, v152, v153
	v_cvt_pk_bf16_f32 v153, v154, v155
	v_cvt_pk_bf16_f32 v154, v148, v149
	v_cvt_pk_bf16_f32 v155, v150, v151
	v_cvt_pk_bf16_f32 v144, v144, v145
	v_cvt_pk_bf16_f32 v145, v146, v147
	v_cvt_pk_bf16_f32 v146, v140, v141
	v_cvt_pk_bf16_f32 v147, v142, v143
	s_waitcnt lgkmcnt(1)
	v_cndmask_b32_e64 v156, v156, 1.0, s[0:1]
	v_cndmask_b32_e64 v157, 1.0, v157, s[2:3]
	v_cndmask_b32_e64 v158, 1.0, v158, s[4:5]
	v_mul_f32_e32 v159, v138, v159
	ds_bpermute_b32 v121, v132, v159
	v_mul_f32_e32 v156, v156, v157
	v_mul_f32_e32 v156, v156, v158
	v_mul_f32_e32 v123, v123, v156
	s_waitcnt lgkmcnt(1)
	v_mul_f32_e32 v120, v119, v120
	v_log_f32_e32 v120, v120
	v_mul_f32_e32 v74, v74, v123
	v_mul_f32_e32 v75, v75, v123
	v_mul_f32_e32 v76, v76, v123
	v_mul_f32_e32 v77, v77, v123
	v_mul_f32_e32 v78, v78, v123
	v_mul_f32_e32 v79, v79, v123
	v_mul_f32_e32 v80, v80, v123
	v_mul_f32_e32 v81, v81, v123
	v_mul_f32_e32 v82, v82, v123
	v_mul_f32_e32 v83, v83, v123
	v_mul_f32_e32 v84, v84, v123
	v_mul_f32_e32 v85, v85, v123
	v_mul_f32_e32 v86, v86, v123
	v_mul_f32_e32 v87, v87, v123
	v_mul_f32_e32 v88, v88, v123
	v_mul_f32_e32 v89, v89, v123
	v_add_f32_e32 v111, v111, v120
	v_cvt_pk_bf16_f32 v86, v86, v87
	v_cvt_pk_bf16_f32 v87, v88, v89
	v_cvt_pk_bf16_f32 v88, v82, v83
	v_cvt_pk_bf16_f32 v89, v84, v85
	v_cvt_pk_bf16_f32 v78, v78, v79
	v_cvt_pk_bf16_f32 v79, v80, v81
	v_cvt_pk_bf16_f32 v80, v74, v75
	v_cvt_pk_bf16_f32 v81, v76, v77
	s_waitcnt lgkmcnt(0)
	v_mul_f32_e32 v121, v159, v121
	v_log_f32_e32 v121, v121
	ds_read_b128 v[116:119], v124 offset:18448
	ds_read_b128 v[140:143], v124 offset:25360
	v_add_f32_e32 v112, v112, v121
	ds_read_b128 v[120:123], v124 offset:20752
	ds_read_b128 v[156:159], v124 offset:23056
	v_mfma_f32_16x16x32_bf16 v[30:33], v[58:61], v[152:155], v[30:33]
	v_mfma_f32_16x16x32_bf16 v[26:29], v[58:61], v[86:89], v[26:29]
	v_mfma_f32_16x16x32_bf16 v[38:41], v[62:65], v[152:155], v[38:41]
	v_mfma_f32_16x16x32_bf16 v[34:37], v[62:65], v[86:89], v[34:37]
	v_mfma_f32_16x16x32_bf16 v[46:49], v[66:69], v[152:155], v[46:49]
	v_mfma_f32_16x16x32_bf16 v[42:45], v[66:69], v[86:89], v[42:45]
	v_mfma_f32_16x16x32_bf16 v[50:53], v[70:73], v[152:155], v[50:53]
	v_mfma_f32_16x16x32_bf16 v[54:57], v[70:73], v[86:89], v[54:57]
	s_waitcnt lgkmcnt(3)
	v_mfma_f32_16x16x32_bf16 v[30:33], v[116:119], v[144:147], v[30:33]
	v_mfma_f32_16x16x32_bf16 v[26:29], v[116:119], v[78:81], v[26:29]
	s_waitcnt lgkmcnt(2)
	v_mfma_f32_16x16x32_bf16 v[50:53], v[140:143], v[144:147], v[50:53]
	v_mfma_f32_16x16x32_bf16 v[54:57], v[140:143], v[78:81], v[54:57]
	s_waitcnt lgkmcnt(1)
	v_mfma_f32_16x16x32_bf16 v[38:41], v[120:123], v[144:147], v[38:41]
	v_mfma_f32_16x16x32_bf16 v[34:37], v[120:123], v[78:81], v[34:37]
	s_waitcnt lgkmcnt(0)
	v_mfma_f32_16x16x32_bf16 v[46:49], v[156:159], v[144:147], v[46:49]
	v_mfma_f32_16x16x32_bf16 v[42:45], v[156:159], v[78:81], v[42:45]
	s_branch .LBB0_709
